# v20 + K-loop MFMA segment edges trimmed: redundant lgkmcnt(0) after barrier removed, setprio raise moved before barrier, lower moved after closing barrier, mid pair removed
# speedup vs baseline: 1.0040x; 1.0022x over previous
; #define PG8_WAIT_V(n) asm volatile("s_waitcnt vmcnt(" #n ")" ::: "memory")
; #define PG8_WAIT_L(n) asm volatile("s_waitcnt lgkmcnt(" #n ")" ::: "memory")
; #define PG8_BAR __builtin_amdgcn_s_barrier()
; #define PG8_SCHED __builtin_amdgcn_sched_barrier(0)
;     ...
;             PG8_LDB(B0, 0, 0); PG8_LDB(B1, 0, 1); PG8_SCHED; PG8_LDA(At, 0, 0); PG8_STAGE(PG8_SA(1, 1), a1 + hstepA, voffA);
;             PG8_WAIT_V(8); PG8_WAIT_L(0); PG8_BAR; PG8_MMA(0, 0, At, B0); PG8_MMA(0, 1, At, B1); PG8_BAR; PG8_SCHED;
;             if constexpr (!HALFU) PG8_LDA(At, 0, 1); PG8_STAGE(PG8_SB(0, 0), b2, voffB); PG8_STAGE(PG8_SB(0, 1), b2 + hstep, voffB); PG8_STAGE(PG8_SA(0, 0), a2, voffA);
;             PG8_WAIT_V(8); PG8_WAIT_L(0); PG8_BAR; if constexpr (!HALFU) { PG8_MMA(1, 0, At, B0); PG8_MMA(1, 1, At, B1); } PG8_BAR; PG8_SCHED;
.LBB0_317:
	s_add_u32 s98, s14, 0x80
	s_addc_u32 s99, s15, 0
	s_mov_b32 m0, s49
	s_nop 0
	global_load_lds_dwordx4 v252, s[98:99]
	s_mov_b32 m0, s50
	s_nop 0
	global_load_lds_dwordx4 v146, s[98:99]
	ds_read_b128 v[128:131], v155
	ds_read_b128 v[132:135], v155 offset:1024
	ds_read_b128 v[164:167], v155 offset:2048
	ds_read_b128 v[168:171], v155 offset:3072
	ds_read_b128 v[172:175], v156
	ds_read_b128 v[176:179], v156 offset:1024
	ds_read_b128 v[180:183], v156 offset:2048
	ds_read_b128 v[184:187], v156 offset:3072
	s_add_u32 s30, s14, 0x100
	s_addc_u32 s31, s15, 0
	s_cmp_eq_u32 s58, 28
	s_cselect_b32 s38, s23, s30
	s_cselect_b32 s39, s7, s31
	s_cselect_b32 s36, s55, s56
	s_cselect_b32 s37, s21, s57
	s_add_u32 s34, s38, 0x80
	s_addc_u32 s35, s39, 0
	s_add_u32 s14, s14, 0x80080
	s_addc_u32 s15, s15, 0
	s_add_i32 m0, s29, 0xc000
	ds_read_b128 v[188:191], v157
	ds_read_b128 v[192:195], v157 offset:1024
	ds_read_b128 v[196:199], v157 offset:2048
	ds_read_b128 v[200:203], v157 offset:3072
	ds_read_b128 v[204:207], v157 offset:4096
	ds_read_b128 v[208:211], v157 offset:5120
	ds_read_b128 v[212:215], v157 offset:6144
	ds_read_b128 v[216:219], v157 offset:7168
	global_load_lds_dwordx4 v252, s[14:15]
	s_add_i32 m0, s29, 0xe000
	s_nop 0
	global_load_lds_dwordx4 v146, s[14:15]
	s_waitcnt vmcnt(8)
	s_waitcnt lgkmcnt(0)
	s_setprio 1
	s_barrier
	v_mfma_scale_f32_16x16x128_f8f6f4 v[124:127], v[128:135], v[188:195], v[124:127], v158, v158 op_sel_hi:[0,0,0]
	v_mfma_scale_f32_16x16x128_f8f6f4 v[120:123], v[164:171], v[188:195], v[120:123], v158, v158 op_sel_hi:[0,0,0]
	v_mfma_scale_f32_16x16x128_f8f6f4 v[108:111], v[128:135], v[196:203], v[108:111], v158, v158 op_sel_hi:[0,0,0]
	v_mfma_scale_f32_16x16x128_f8f6f4 v[104:107], v[164:171], v[196:203], v[104:107], v158, v158 op_sel_hi:[0,0,0]
	v_mfma_scale_f32_16x16x128_f8f6f4 v[136:139], v[128:135], v[204:211], v[92:95], v158, v158 op_sel_hi:[0,0,0]
	v_mfma_scale_f32_16x16x128_f8f6f4 v[220:223], v[164:171], v[204:211], v[88:91], v158, v158 op_sel_hi:[0,0,0]
	v_mfma_scale_f32_16x16x128_f8f6f4 v[224:227], v[128:135], v[212:219], v[76:79], v158, v158 op_sel_hi:[0,0,0]
	v_mfma_scale_f32_16x16x128_f8f6f4 v[228:231], v[164:171], v[212:219], v[72:75], v158, v158 op_sel_hi:[0,0,0]
	v_mfma_scale_f32_16x16x128_f8f6f4 v[116:119], v[172:179], v[188:195], v[116:119], v158, v158 op_sel_hi:[0,0,0]
	v_mfma_scale_f32_16x16x128_f8f6f4 v[112:115], v[180:187], v[188:195], v[112:115], v158, v158 op_sel_hi:[0,0,0]
	v_mfma_scale_f32_16x16x128_f8f6f4 v[100:103], v[172:179], v[196:203], v[100:103], v158, v158 op_sel_hi:[0,0,0]
	v_mfma_scale_f32_16x16x128_f8f6f4 v[96:99], v[180:187], v[196:203], v[96:99], v158, v158 op_sel_hi:[0,0,0]
	v_mfma_scale_f32_16x16x128_f8f6f4 v[188:191], v[172:179], v[204:211], v[84:87], v158, v158 op_sel_hi:[0,0,0]
	v_mfma_scale_f32_16x16x128_f8f6f4 v[192:195], v[180:187], v[204:211], v[80:83], v158, v158 op_sel_hi:[0,0,0]
	v_mfma_scale_f32_16x16x128_f8f6f4 v[196:199], v[172:179], v[212:219], v[68:71], v158, v158 op_sel_hi:[0,0,0]
	v_mfma_scale_f32_16x16x128_f8f6f4 v[200:203], v[180:187], v[212:219], v[64:67], v158, v158 op_sel_hi:[0,0,0]
	s_barrier
	s_setprio 0
	s_add_i32 s14, s53, s40
	s_mov_b32 m0, s14
	s_nop 1
	ds_read_b128 v[64:67], v157 offset:16384
	ds_read_b128 v[68:71], v157 offset:17408
	ds_read_b128 v[72:75], v157 offset:18432
	ds_read_b128 v[76:79], v157 offset:19456
	ds_read_b128 v[80:83], v157 offset:20480
	ds_read_b128 v[84:87], v157 offset:21504
	ds_read_b128 v[88:91], v157 offset:22528
	ds_read_b128 v[92:95], v157 offset:23552
	global_load_lds_dwordx4 v144, s[36:37]
	s_add_i32 m0, s14, 0x2000
	s_add_u32 s14, s36, 0x80000
	s_addc_u32 s15, s37, 0
	s_add_i32 s59, s54, s40
	global_load_lds_dwordx4 v148, s[36:37]
	s_mov_b32 m0, s59
	s_nop 0
	global_load_lds_dwordx4 v144, s[14:15]
	s_add_i32 m0, s59, 0x2000
	s_nop 0
	global_load_lds_dwordx4 v148, s[14:15]
	s_waitcnt vmcnt(4)
	s_waitcnt lgkmcnt(0)
	s_setprio 1
	s_barrier
	v_mfma_scale_f32_16x16x128_f8f6f4 v[60:63], v[128:135], v[64:71], v[60:63], v158, v158 op_sel_hi:[0,0,0]
	v_mfma_scale_f32_16x16x128_f8f6f4 v[56:59], v[164:171], v[64:71], v[56:59], v158, v158 op_sel_hi:[0,0,0]
	v_mfma_scale_f32_16x16x128_f8f6f4 v[204:207], v[128:135], v[72:79], v[44:47], v158, v158 op_sel_hi:[0,0,0]
	v_mfma_scale_f32_16x16x128_f8f6f4 v[208:211], v[164:171], v[72:79], v[40:43], v158, v158 op_sel_hi:[0,0,0]
	v_mfma_scale_f32_16x16x128_f8f6f4 v[212:215], v[128:135], v[80:87], v[28:31], v158, v158 op_sel_hi:[0,0,0]
	v_mfma_scale_f32_16x16x128_f8f6f4 v[216:219], v[164:171], v[80:87], v[24:27], v158, v158 op_sel_hi:[0,0,0]
	v_mfma_scale_f32_16x16x128_f8f6f4 v[232:235], v[128:135], v[88:95], v[12:15], v158, v158 op_sel_hi:[0,0,0]
	v_mfma_scale_f32_16x16x128_f8f6f4 v[236:239], v[164:171], v[88:95], v[8:11], v158, v158 op_sel_hi:[0,0,0]
	v_mfma_scale_f32_16x16x128_f8f6f4 v[52:55], v[172:179], v[64:71], v[52:55], v158, v158 op_sel_hi:[0,0,0]
	v_mfma_scale_f32_16x16x128_f8f6f4 v[48:51], v[180:187], v[64:71], v[48:51], v158, v158 op_sel_hi:[0,0,0]
	v_mfma_scale_f32_16x16x128_f8f6f4 v[240:243], v[172:179], v[72:79], v[36:39], v158, v158 op_sel_hi:[0,0,0]
	v_mfma_scale_f32_16x16x128_f8f6f4 v[244:247], v[180:187], v[72:79], v[32:35], v158, v158 op_sel_hi:[0,0,0]
	v_mfma_scale_f32_16x16x128_f8f6f4 v[248:251], v[172:179], v[80:87], v[20:23], v158, v158 op_sel_hi:[0,0,0]
	v_mfma_scale_f32_16x16x128_f8f6f4 v[150:153], v[180:187], v[80:87], v[16:19], v158, v158 op_sel_hi:[0,0,0]
	v_mfma_scale_f32_16x16x128_f8f6f4 v[160:163], v[172:179], v[88:95], v[4:7], v158, v158 op_sel_hi:[0,0,0]
	v_mfma_scale_f32_16x16x128_f8f6f4 v[140:143], v[180:187], v[88:95], v[0:3], v158, v158 op_sel_hi:[0,0,0]
	s_barrier
; #define PG8_WAIT_V(n) asm volatile("s_waitcnt vmcnt(" #n ")" ::: "memory")
; #define PG8_WAIT_L(n) asm volatile("s_waitcnt lgkmcnt(" #n ")" ::: "memory")
; #define PG8_BAR __builtin_amdgcn_s_barrier()
; #define PG8_SCHED __builtin_amdgcn_sched_barrier(0)
;     ...
;         for (int t = 0; t < nt; t += 2) {
;             const bool last = (t == nt - 2);
;             const char* a1 = cA + (size_t)(t + 1) * kstep;
;             const char* a2 = last ? nA : cA + (size_t)(t + 2) * kstep; const char* b2 = last ? nB : cB + (size_t)(t + 2) * kstep;
;             const char* a3 = a2 + kstep; const char* b3 = b2 + kstep;
;             if (last && has_next) S.a_ready(nxt);
;     ...
;             PG8_LDB(B0, 1, 0); PG8_LDB(B1, 1, 1); PG8_SCHED; PG8_LDA(At, 1, 0); PG8_STAGE(PG8_SA(0, 1), a2 + hstepA, voffA);
;             PG8_WAIT_V(8); PG8_WAIT_L(0); PG8_BAR; PG8_MMA(0, 0, At, B0); PG8_MMA(0, 1, At, B1); PG8_BAR; PG8_SCHED;
;             if constexpr (!HALFU) PG8_LDA(At, 1, 1); PG8_STAGE(PG8_SB(1, 0), b3, voffB); PG8_STAGE(PG8_SB(1, 1), b3 + hstep, voffB); PG8_STAGE(PG8_SA(1, 0), a3, voffA);
;             PG8_WAIT_V(8); PG8_WAIT_L(0); PG8_BAR; if constexpr (!HALFU) { PG8_MMA(1, 0, At, B0); PG8_MMA(1, 1, At, B1); } PG8_BAR; PG8_SCHED;
	s_setprio 0
	s_mov_b32 m0, s29
	s_nop 0
	global_load_lds_dwordx4 v252, s[38:39]
	s_mov_b32 m0, s41
	s_nop 0
	global_load_lds_dwordx4 v146, s[38:39]
	s_add_i32 s59, 0, 0x18000
	v_add_u32_e32 v8, s59, v154
	s_add_i32 s60, 0, 0x1c000
	s_nop 1
	ds_read_b128 v[0:3], v8
	ds_read_b128 v[4:7], v8 offset:1024
	ds_read_b128 v[16:19], v8 offset:2048
	ds_read_b128 v[20:23], v8 offset:3072
	v_add_u32_e32 v8, s60, v154
	ds_read_b128 v[128:131], v8
	ds_read_b128 v[132:135], v8 offset:1024
	ds_read_b128 v[164:167], v8 offset:2048
	ds_read_b128 v[168:171], v8 offset:3072
	s_add_u32 s14, s38, 0x80000
	s_addc_u32 s15, s39, 0
	s_mov_b32 m0, s42
	ds_read_b128 v[8:11], v157 offset:32768
	ds_read_b128 v[12:15], v157 offset:33792
	ds_read_b128 v[24:27], v157 offset:34816
	ds_read_b128 v[28:31], v157 offset:35840
	ds_read_b128 v[32:35], v157 offset:36864
	ds_read_b128 v[36:39], v157 offset:37888
	ds_read_b128 v[40:43], v157 offset:38912
	ds_read_b128 v[44:47], v157 offset:39936
	global_load_lds_dwordx4 v252, s[14:15]
	s_mov_b32 m0, s43
	s_nop 0
	global_load_lds_dwordx4 v146, s[14:15]
	s_waitcnt vmcnt(8)
	s_waitcnt lgkmcnt(0)
	s_setprio 1
	s_barrier
	v_mfma_scale_f32_16x16x128_f8f6f4 v[124:127], v[0:7], v[8:15], v[124:127], v158, v158 op_sel_hi:[0,0,0]
	v_mfma_scale_f32_16x16x128_f8f6f4 v[120:123], v[16:23], v[8:15], v[120:123], v158, v158 op_sel_hi:[0,0,0]
	v_mfma_scale_f32_16x16x128_f8f6f4 v[108:111], v[0:7], v[24:31], v[108:111], v158, v158 op_sel_hi:[0,0,0]
	v_mfma_scale_f32_16x16x128_f8f6f4 v[104:107], v[16:23], v[24:31], v[104:107], v158, v158 op_sel_hi:[0,0,0]
	v_mfma_scale_f32_16x16x128_f8f6f4 v[92:95], v[0:7], v[32:39], v[136:139], v158, v158 op_sel_hi:[0,0,0]
	v_mfma_scale_f32_16x16x128_f8f6f4 v[88:91], v[16:23], v[32:39], v[220:223], v158, v158 op_sel_hi:[0,0,0]
	v_mfma_scale_f32_16x16x128_f8f6f4 v[76:79], v[0:7], v[40:47], v[224:227], v158, v158 op_sel_hi:[0,0,0]
	v_mfma_scale_f32_16x16x128_f8f6f4 v[72:75], v[16:23], v[40:47], v[228:231], v158, v158 op_sel_hi:[0,0,0]
	v_mfma_scale_f32_16x16x128_f8f6f4 v[116:119], v[128:135], v[8:15], v[116:119], v158, v158 op_sel_hi:[0,0,0]
	v_mfma_scale_f32_16x16x128_f8f6f4 v[112:115], v[164:171], v[8:15], v[112:115], v158, v158 op_sel_hi:[0,0,0]
	v_mfma_scale_f32_16x16x128_f8f6f4 v[100:103], v[128:135], v[24:31], v[100:103], v158, v158 op_sel_hi:[0,0,0]
	v_mfma_scale_f32_16x16x128_f8f6f4 v[96:99], v[164:171], v[24:31], v[96:99], v158, v158 op_sel_hi:[0,0,0]
	v_mfma_scale_f32_16x16x128_f8f6f4 v[84:87], v[128:135], v[32:39], v[188:191], v158, v158 op_sel_hi:[0,0,0]
	v_mfma_scale_f32_16x16x128_f8f6f4 v[80:83], v[164:171], v[32:39], v[192:195], v158, v158 op_sel_hi:[0,0,0]
	v_mfma_scale_f32_16x16x128_f8f6f4 v[68:71], v[128:135], v[40:47], v[196:199], v158, v158 op_sel_hi:[0,0,0]
	v_mfma_scale_f32_16x16x128_f8f6f4 v[64:67], v[164:171], v[40:47], v[200:203], v158, v158 op_sel_hi:[0,0,0]
	s_barrier
	s_setprio 0
	s_add_u32 s14, s36, 0x80
	s_addc_u32 s15, s37, 0
	s_add_i32 s38, s59, s40
	s_mov_b32 m0, s38
	ds_read_b128 v[32:35], v157 offset:49152
	ds_read_b128 v[36:39], v157 offset:50176
	ds_read_b128 v[172:175], v157 offset:51200
	ds_read_b128 v[176:179], v157 offset:52224
	ds_read_b128 v[180:183], v157 offset:53248
	ds_read_b128 v[184:187], v157 offset:54272
	ds_read_b128 v[188:191], v157 offset:55296
	ds_read_b128 v[192:195], v157 offset:56320
	global_load_lds_dwordx4 v144, s[14:15]
	s_add_i32 m0, s38, 0x2000
	v_lshl_add_u64 v[8:9], s[14:15], 0, v[148:149]
	s_add_u32 s14, s36, 0x80080
	s_addc_u32 s15, s37, 0
	s_add_i32 s36, s60, s40
	global_load_lds_dwordx4 v[8:9], off
	s_mov_b32 m0, s36
	s_nop 0
	global_load_lds_dwordx4 v144, s[14:15]
	s_add_i32 m0, s36, 0x2000
	s_nop 0
	global_load_lds_dwordx4 v148, s[14:15]
	s_waitcnt vmcnt(4)
	s_waitcnt lgkmcnt(0)
	s_setprio 1
	s_barrier
	v_mfma_scale_f32_16x16x128_f8f6f4 v[60:63], v[0:7], v[32:39], v[60:63], v158, v158 op_sel_hi:[0,0,0]
	v_mfma_scale_f32_16x16x128_f8f6f4 v[56:59], v[16:23], v[32:39], v[56:59], v158, v158 op_sel_hi:[0,0,0]
	v_mfma_scale_f32_16x16x128_f8f6f4 v[44:47], v[0:7], v[172:179], v[204:207], v158, v158 op_sel_hi:[0,0,0]
	v_mfma_scale_f32_16x16x128_f8f6f4 v[40:43], v[16:23], v[172:179], v[208:211], v158, v158 op_sel_hi:[0,0,0]
	v_mfma_scale_f32_16x16x128_f8f6f4 v[28:31], v[0:7], v[180:187], v[212:215], v158, v158 op_sel_hi:[0,0,0]
	v_mfma_scale_f32_16x16x128_f8f6f4 v[24:27], v[16:23], v[180:187], v[216:219], v158, v158 op_sel_hi:[0,0,0]
	v_mfma_scale_f32_16x16x128_f8f6f4 v[12:15], v[0:7], v[188:195], v[232:235], v158, v158 op_sel_hi:[0,0,0]
	v_mfma_scale_f32_16x16x128_f8f6f4 v[8:11], v[16:23], v[188:195], v[236:239], v158, v158 op_sel_hi:[0,0,0]
	v_mfma_scale_f32_16x16x128_f8f6f4 v[52:55], v[128:135], v[32:39], v[52:55], v158, v158 op_sel_hi:[0,0,0]
	v_mfma_scale_f32_16x16x128_f8f6f4 v[48:51], v[164:171], v[32:39], v[48:51], v158, v158 op_sel_hi:[0,0,0]
	v_mfma_scale_f32_16x16x128_f8f6f4 v[36:39], v[128:135], v[172:179], v[240:243], v158, v158 op_sel_hi:[0,0,0]
	v_mfma_scale_f32_16x16x128_f8f6f4 v[32:35], v[164:171], v[172:179], v[244:247], v158, v158 op_sel_hi:[0,0,0]
	v_mfma_scale_f32_16x16x128_f8f6f4 v[20:23], v[128:135], v[180:187], v[248:251], v158, v158 op_sel_hi:[0,0,0]
	v_mfma_scale_f32_16x16x128_f8f6f4 v[16:19], v[164:171], v[180:187], v[150:153], v158, v158 op_sel_hi:[0,0,0]
	v_mfma_scale_f32_16x16x128_f8f6f4 v[4:7], v[128:135], v[188:195], v[160:163], v158, v158 op_sel_hi:[0,0,0]
	v_mfma_scale_f32_16x16x128_f8f6f4 v[0:3], v[164:171], v[188:195], v[140:143], v158, v158 op_sel_hi:[0,0,0]
	s_barrier
	s_setprio 0
	s_add_i32 s58, s58, 2
	s_add_u32 s56, s56, 0x100
	s_addc_u32 s57, s57, 0
	s_cmp_gt_u32 s58, 29
	s_mov_b64 s[14:15], s[30:31]
	s_cbranch_scc0 .LBB0_317
	s_and_b64 vcc, exec, s[16:17]
	s_cbranch_vccz .LBB0_320
	s_barrier

; #define PG8_WAIT_V(n) asm volatile("s_waitcnt vmcnt(" #n ")" ::: "memory")
; #define PG8_WAIT_L(n) asm volatile("s_waitcnt lgkmcnt(" #n ")" ::: "memory")
; #define PG8_BAR __builtin_amdgcn_s_barrier()
; #define PG8_SCHED __builtin_amdgcn_sched_barrier(0)
;     ...
;             PG8_LDB(B0, 0, 0); PG8_LDB(B1, 0, 1); PG8_SCHED; PG8_LDA(At, 0, 0); PG8_STAGE(PG8_SA(1, 1), a1 + hstepA, voffA);
;             PG8_WAIT_V(8); PG8_WAIT_L(0); PG8_BAR; PG8_MMA(0, 0, At, B0); PG8_MMA(0, 1, At, B1); PG8_BAR; PG8_SCHED;
;             if constexpr (!HALFU) PG8_LDA(At, 0, 1); PG8_STAGE(PG8_SB(0, 0), b2, voffB); PG8_STAGE(PG8_SB(0, 1), b2 + hstep, voffB); PG8_STAGE(PG8_SA(0, 0), a2, voffA);
;             PG8_WAIT_V(8); PG8_WAIT_L(0); PG8_BAR; if constexpr (!HALFU) { PG8_MMA(1, 0, At, B0); PG8_MMA(1, 1, At, B1); } PG8_BAR; PG8_SCHED;
.LBB0_542:
	s_add_u32 s98, s28, 0x80
	s_addc_u32 s99, s29, 0
	s_mov_b32 m0, s53
	s_nop 0
	global_load_lds_dwordx4 v128, s[98:99]
	s_mov_b32 m0, s54
	s_nop 0
	global_load_lds_dwordx4 v130, s[98:99]
	ds_read_b128 v[142:145], v137
	ds_read_b128 v[146:149], v137 offset:1024
	ds_read_b128 v[150:153], v137 offset:2048
	ds_read_b128 v[154:157], v137 offset:3072
	ds_read_b128 v[158:161], v138
	ds_read_b128 v[162:165], v138 offset:1024
	ds_read_b128 v[166:169], v138 offset:2048
	ds_read_b128 v[170:173], v138 offset:3072
	s_add_u32 s30, s28, 0x100
	s_addc_u32 s31, s29, 0
	s_cmp_eq_u32 s61, 12
	s_cselect_b32 s40, s57, s30
	s_cselect_b32 s41, s23, s31
	s_cselect_b32 s38, s58, s59
	s_cselect_b32 s39, s21, s60
	s_add_u32 s36, s40, 0x80
	s_addc_u32 s37, s41, 0
	s_add_u32 s28, s28, 0x40080
	s_addc_u32 s29, s29, 0
	s_add_i32 m0, s45, 0xc000
	ds_read_b128 v[174:177], v139
	ds_read_b128 v[178:181], v139 offset:1024
	ds_read_b128 v[182:185], v139 offset:2048
	ds_read_b128 v[186:189], v139 offset:3072
	ds_read_b128 v[190:193], v139 offset:4096
	ds_read_b128 v[194:197], v139 offset:5120
	ds_read_b128 v[198:201], v139 offset:6144
	ds_read_b128 v[202:205], v139 offset:7168
	global_load_lds_dwordx4 v128, s[28:29]
	s_add_i32 m0, s45, 0xe000
	s_nop 0
	global_load_lds_dwordx4 v130, s[28:29]
	s_waitcnt vmcnt(8)
	s_waitcnt lgkmcnt(0)
	s_setprio 1
	s_barrier
	v_mfma_scale_f32_16x16x128_f8f6f4 v[124:127], v[142:149], v[174:181], v[124:127], v140, v140 op_sel_hi:[0,0,0]
	v_mfma_scale_f32_16x16x128_f8f6f4 v[120:123], v[150:157], v[174:181], v[120:123], v140, v140 op_sel_hi:[0,0,0]
	v_mfma_scale_f32_16x16x128_f8f6f4 v[108:111], v[142:149], v[182:189], v[108:111], v140, v140 op_sel_hi:[0,0,0]
	v_mfma_scale_f32_16x16x128_f8f6f4 v[104:107], v[150:157], v[182:189], v[104:107], v140, v140 op_sel_hi:[0,0,0]
	v_mfma_scale_f32_16x16x128_f8f6f4 v[96:99], v[142:149], v[190:197], v[96:99], v140, v140 op_sel_hi:[0,0,0]
	v_mfma_scale_f32_16x16x128_f8f6f4 v[206:209], v[150:157], v[190:197], v[88:91], v140, v140 op_sel_hi:[0,0,0]
	v_mfma_scale_f32_16x16x128_f8f6f4 v[210:213], v[142:149], v[198:205], v[80:83], v140, v140 op_sel_hi:[0,0,0]
	v_mfma_scale_f32_16x16x128_f8f6f4 v[214:217], v[150:157], v[198:205], v[72:75], v140, v140 op_sel_hi:[0,0,0]
	v_mfma_scale_f32_16x16x128_f8f6f4 v[116:119], v[158:165], v[174:181], v[116:119], v140, v140 op_sel_hi:[0,0,0]
	v_mfma_scale_f32_16x16x128_f8f6f4 v[112:115], v[166:173], v[174:181], v[112:115], v140, v140 op_sel_hi:[0,0,0]
	v_mfma_scale_f32_16x16x128_f8f6f4 v[100:103], v[158:165], v[182:189], v[100:103], v140, v140 op_sel_hi:[0,0,0]
	v_mfma_scale_f32_16x16x128_f8f6f4 v[174:177], v[166:173], v[182:189], v[92:95], v140, v140 op_sel_hi:[0,0,0]
	v_mfma_scale_f32_16x16x128_f8f6f4 v[178:181], v[158:165], v[190:197], v[84:87], v140, v140 op_sel_hi:[0,0,0]
	v_mfma_scale_f32_16x16x128_f8f6f4 v[182:185], v[166:173], v[190:197], v[76:79], v140, v140 op_sel_hi:[0,0,0]
	v_mfma_scale_f32_16x16x128_f8f6f4 v[186:189], v[158:165], v[198:205], v[68:71], v140, v140 op_sel_hi:[0,0,0]
	v_mfma_scale_f32_16x16x128_f8f6f4 v[190:193], v[166:173], v[198:205], v[64:67], v140, v140 op_sel_hi:[0,0,0]
	s_barrier
	s_setprio 0
	s_add_i32 s28, s55, s43
	s_mov_b32 m0, s28
	s_nop 1
	ds_read_b128 v[64:67], v139 offset:16384
	ds_read_b128 v[68:71], v139 offset:17408
	ds_read_b128 v[72:75], v139 offset:18432
	ds_read_b128 v[76:79], v139 offset:19456
	ds_read_b128 v[80:83], v139 offset:20480
	ds_read_b128 v[84:87], v139 offset:21504
	ds_read_b128 v[88:91], v139 offset:22528
	ds_read_b128 v[92:95], v139 offset:23552
	global_load_lds_dwordx4 v128, s[38:39]
	s_add_i32 m0, s28, 0x2000
	s_add_u32 s28, s38, 0x40000
	s_addc_u32 s29, s39, 0
	s_add_i32 s62, s56, s43
	global_load_lds_dwordx4 v130, s[38:39]
	s_mov_b32 m0, s62
	s_nop 0
	global_load_lds_dwordx4 v128, s[28:29]
	s_add_i32 m0, s62, 0x2000
	s_nop 0
	global_load_lds_dwordx4 v130, s[28:29]
	s_waitcnt vmcnt(4)
	s_waitcnt lgkmcnt(0)
	s_setprio 1
	s_barrier
	v_mfma_scale_f32_16x16x128_f8f6f4 v[60:63], v[142:149], v[64:71], v[60:63], v140, v140 op_sel_hi:[0,0,0]
	v_mfma_scale_f32_16x16x128_f8f6f4 v[56:59], v[150:157], v[64:71], v[56:59], v140, v140 op_sel_hi:[0,0,0]
	v_mfma_scale_f32_16x16x128_f8f6f4 v[48:51], v[142:149], v[72:79], v[48:51], v140, v140 op_sel_hi:[0,0,0]
	v_mfma_scale_f32_16x16x128_f8f6f4 v[194:197], v[150:157], v[72:79], v[40:43], v140, v140 op_sel_hi:[0,0,0]
	v_mfma_scale_f32_16x16x128_f8f6f4 v[198:201], v[142:149], v[80:87], v[32:35], v140, v140 op_sel_hi:[0,0,0]
	v_mfma_scale_f32_16x16x128_f8f6f4 v[202:205], v[150:157], v[80:87], v[24:27], v140, v140 op_sel_hi:[0,0,0]
	v_mfma_scale_f32_16x16x128_f8f6f4 v[218:221], v[142:149], v[88:95], v[16:19], v140, v140 op_sel_hi:[0,0,0]
	v_mfma_scale_f32_16x16x128_f8f6f4 v[222:225], v[150:157], v[88:95], v[8:11], v140, v140 op_sel_hi:[0,0,0]
	v_mfma_scale_f32_16x16x128_f8f6f4 v[52:55], v[158:165], v[64:71], v[52:55], v140, v140 op_sel_hi:[0,0,0]
	v_mfma_scale_f32_16x16x128_f8f6f4 v[226:229], v[166:173], v[64:71], v[44:47], v140, v140 op_sel_hi:[0,0,0]
	v_mfma_scale_f32_16x16x128_f8f6f4 v[230:233], v[158:165], v[72:79], v[36:39], v140, v140 op_sel_hi:[0,0,0]
	v_mfma_scale_f32_16x16x128_f8f6f4 v[234:237], v[166:173], v[72:79], v[28:31], v140, v140 op_sel_hi:[0,0,0]
	v_mfma_scale_f32_16x16x128_f8f6f4 v[238:241], v[158:165], v[80:87], v[20:23], v140, v140 op_sel_hi:[0,0,0]
	v_mfma_scale_f32_16x16x128_f8f6f4 v[242:245], v[166:173], v[80:87], v[12:15], v140, v140 op_sel_hi:[0,0,0]
	v_mfma_scale_f32_16x16x128_f8f6f4 v[246:249], v[158:165], v[88:95], v[4:7], v140, v140 op_sel_hi:[0,0,0]
	v_mfma_scale_f32_16x16x128_f8f6f4 v[250:253], v[166:173], v[88:95], v[0:3], v140, v140 op_sel_hi:[0,0,0]
	s_barrier
; #define PG8_WAIT_V(n) asm volatile("s_waitcnt vmcnt(" #n ")" ::: "memory")
; #define PG8_WAIT_L(n) asm volatile("s_waitcnt lgkmcnt(" #n ")" ::: "memory")
; #define PG8_BAR __builtin_amdgcn_s_barrier()
; #define PG8_SCHED __builtin_amdgcn_sched_barrier(0)
;     ...
;         for (int t = 0; t < nt; t += 2) {
;             const bool last = (t == nt - 2);
;             const char* a1 = cA + (size_t)(t + 1) * kstep;
;             const char* a2 = last ? nA : cA + (size_t)(t + 2) * kstep; const char* b2 = last ? nB : cB + (size_t)(t + 2) * kstep;
;             const char* a3 = a2 + kstep; const char* b3 = b2 + kstep;
;             if (last && has_next) S.a_ready(nxt);
;     ...
;             PG8_LDB(B0, 1, 0); PG8_LDB(B1, 1, 1); PG8_SCHED; PG8_LDA(At, 1, 0); PG8_STAGE(PG8_SA(0, 1), a2 + hstepA, voffA);
;             PG8_WAIT_V(8); PG8_WAIT_L(0); PG8_BAR; PG8_MMA(0, 0, At, B0); PG8_MMA(0, 1, At, B1); PG8_BAR; PG8_SCHED;
;             if constexpr (!HALFU) PG8_LDA(At, 1, 1); PG8_STAGE(PG8_SB(1, 0), b3, voffB); PG8_STAGE(PG8_SB(1, 1), b3 + hstep, voffB); PG8_STAGE(PG8_SA(1, 0), a3, voffA);
;             PG8_WAIT_V(8); PG8_WAIT_L(0); PG8_BAR; if constexpr (!HALFU) { PG8_MMA(1, 0, At, B0); PG8_MMA(1, 1, At, B1); } PG8_BAR; PG8_SCHED;
	s_setprio 0
	s_mov_b32 m0, s45
	s_nop 0
	global_load_lds_dwordx4 v128, s[40:41]
	s_mov_b32 m0, s46
	s_nop 0
	global_load_lds_dwordx4 v130, s[40:41]
	s_add_i32 s62, 0, 0x18000
	s_add_i32 s63, 0, 0x1c000
	s_nop 0
	v_add_u32_e32 v12, s62, v136
	v_add_u32_e32 v16, s63, v136
	ds_read_b128 v[0:3], v12
	ds_read_b128 v[4:7], v12 offset:1024
	ds_read_b128 v[8:11], v12 offset:2048
	ds_read_b128 v[12:15], v12 offset:3072
	ds_read_b128 v[142:145], v16
	ds_read_b128 v[146:149], v16 offset:1024
	ds_read_b128 v[150:153], v16 offset:2048
	ds_read_b128 v[154:157], v16 offset:3072
	s_add_u32 s28, s40, 0x40000
	s_addc_u32 s29, s41, 0
	s_mov_b32 m0, s47
	ds_read_b128 v[16:19], v139 offset:32768
	ds_read_b128 v[20:23], v139 offset:33792
	ds_read_b128 v[24:27], v139 offset:34816
	ds_read_b128 v[28:31], v139 offset:35840
	ds_read_b128 v[32:35], v139 offset:36864
	ds_read_b128 v[36:39], v139 offset:37888
	ds_read_b128 v[40:43], v139 offset:38912
	ds_read_b128 v[44:47], v139 offset:39936
	global_load_lds_dwordx4 v128, s[28:29]
	s_mov_b32 m0, s48
	s_nop 0
	global_load_lds_dwordx4 v130, s[28:29]
	s_waitcnt vmcnt(8)
	s_waitcnt lgkmcnt(0)
	s_setprio 1
	s_barrier
	v_mfma_scale_f32_16x16x128_f8f6f4 v[124:127], v[0:7], v[16:23], v[124:127], v140, v140 op_sel_hi:[0,0,0]
	v_mfma_scale_f32_16x16x128_f8f6f4 v[120:123], v[8:15], v[16:23], v[120:123], v140, v140 op_sel_hi:[0,0,0]
	v_mfma_scale_f32_16x16x128_f8f6f4 v[108:111], v[0:7], v[24:31], v[108:111], v140, v140 op_sel_hi:[0,0,0]
	v_mfma_scale_f32_16x16x128_f8f6f4 v[104:107], v[8:15], v[24:31], v[104:107], v140, v140 op_sel_hi:[0,0,0]
	v_mfma_scale_f32_16x16x128_f8f6f4 v[96:99], v[0:7], v[32:39], v[96:99], v140, v140 op_sel_hi:[0,0,0]
	v_mfma_scale_f32_16x16x128_f8f6f4 v[88:91], v[8:15], v[32:39], v[206:209], v140, v140 op_sel_hi:[0,0,0]
	v_mfma_scale_f32_16x16x128_f8f6f4 v[80:83], v[0:7], v[40:47], v[210:213], v140, v140 op_sel_hi:[0,0,0]
	v_mfma_scale_f32_16x16x128_f8f6f4 v[72:75], v[8:15], v[40:47], v[214:217], v140, v140 op_sel_hi:[0,0,0]
	v_mfma_scale_f32_16x16x128_f8f6f4 v[116:119], v[142:149], v[16:23], v[116:119], v140, v140 op_sel_hi:[0,0,0]
	v_mfma_scale_f32_16x16x128_f8f6f4 v[112:115], v[150:157], v[16:23], v[112:115], v140, v140 op_sel_hi:[0,0,0]
	v_mfma_scale_f32_16x16x128_f8f6f4 v[100:103], v[142:149], v[24:31], v[100:103], v140, v140 op_sel_hi:[0,0,0]
	v_mfma_scale_f32_16x16x128_f8f6f4 v[92:95], v[150:157], v[24:31], v[174:177], v140, v140 op_sel_hi:[0,0,0]
	v_mfma_scale_f32_16x16x128_f8f6f4 v[84:87], v[142:149], v[32:39], v[178:181], v140, v140 op_sel_hi:[0,0,0]
	v_mfma_scale_f32_16x16x128_f8f6f4 v[76:79], v[150:157], v[32:39], v[182:185], v140, v140 op_sel_hi:[0,0,0]
	v_mfma_scale_f32_16x16x128_f8f6f4 v[68:71], v[142:149], v[40:47], v[186:189], v140, v140 op_sel_hi:[0,0,0]
	v_mfma_scale_f32_16x16x128_f8f6f4 v[64:67], v[150:157], v[40:47], v[190:193], v140, v140 op_sel_hi:[0,0,0]
	s_barrier
	s_setprio 0
	s_add_u32 s28, s38, 0x80
	s_addc_u32 s29, s39, 0
	s_add_i32 s40, s62, s43
	s_mov_b32 m0, s40
	ds_read_b128 v[158:161], v139 offset:49152
	ds_read_b128 v[162:165], v139 offset:50176
	ds_read_b128 v[166:169], v139 offset:51200
	ds_read_b128 v[170:173], v139 offset:52224
	ds_read_b128 v[174:177], v139 offset:53248
	ds_read_b128 v[178:181], v139 offset:54272
	ds_read_b128 v[182:185], v139 offset:55296
	ds_read_b128 v[186:189], v139 offset:56320
	global_load_lds_dwordx4 v128, s[28:29]
	s_add_i32 m0, s40, 0x2000
	v_lshl_add_u64 v[16:17], s[28:29], 0, v[130:131]
	s_add_u32 s28, s38, 0x40080
	s_addc_u32 s29, s39, 0
	s_add_i32 s38, s63, s43
	global_load_lds_dwordx4 v[16:17], off
	s_mov_b32 m0, s38
	s_nop 0
	global_load_lds_dwordx4 v128, s[28:29]
	s_add_i32 m0, s38, 0x2000
	s_nop 0
	global_load_lds_dwordx4 v130, s[28:29]
	s_waitcnt vmcnt(4)
	s_waitcnt lgkmcnt(0)
	s_setprio 1
	s_barrier
	v_mfma_scale_f32_16x16x128_f8f6f4 v[60:63], v[0:7], v[158:165], v[60:63], v140, v140 op_sel_hi:[0,0,0]
	v_mfma_scale_f32_16x16x128_f8f6f4 v[56:59], v[8:15], v[158:165], v[56:59], v140, v140 op_sel_hi:[0,0,0]
	v_mfma_scale_f32_16x16x128_f8f6f4 v[48:51], v[0:7], v[166:173], v[48:51], v140, v140 op_sel_hi:[0,0,0]
	v_mfma_scale_f32_16x16x128_f8f6f4 v[40:43], v[8:15], v[166:173], v[194:197], v140, v140 op_sel_hi:[0,0,0]
	v_mfma_scale_f32_16x16x128_f8f6f4 v[32:35], v[0:7], v[174:181], v[198:201], v140, v140 op_sel_hi:[0,0,0]
	v_mfma_scale_f32_16x16x128_f8f6f4 v[24:27], v[8:15], v[174:181], v[202:205], v140, v140 op_sel_hi:[0,0,0]
	v_mfma_scale_f32_16x16x128_f8f6f4 v[16:19], v[0:7], v[182:189], v[218:221], v140, v140 op_sel_hi:[0,0,0]
	v_mfma_scale_f32_16x16x128_f8f6f4 v[8:11], v[8:15], v[182:189], v[222:225], v140, v140 op_sel_hi:[0,0,0]
	v_mfma_scale_f32_16x16x128_f8f6f4 v[52:55], v[142:149], v[158:165], v[52:55], v140, v140 op_sel_hi:[0,0,0]
	v_mfma_scale_f32_16x16x128_f8f6f4 v[44:47], v[150:157], v[158:165], v[226:229], v140, v140 op_sel_hi:[0,0,0]
	v_mfma_scale_f32_16x16x128_f8f6f4 v[36:39], v[142:149], v[166:173], v[230:233], v140, v140 op_sel_hi:[0,0,0]
	v_mfma_scale_f32_16x16x128_f8f6f4 v[28:31], v[150:157], v[166:173], v[234:237], v140, v140 op_sel_hi:[0,0,0]
	v_mfma_scale_f32_16x16x128_f8f6f4 v[20:23], v[142:149], v[174:181], v[238:241], v140, v140 op_sel_hi:[0,0,0]
	v_mfma_scale_f32_16x16x128_f8f6f4 v[12:15], v[150:157], v[174:181], v[242:245], v140, v140 op_sel_hi:[0,0,0]
	v_mfma_scale_f32_16x16x128_f8f6f4 v[4:7], v[142:149], v[182:189], v[246:249], v140, v140 op_sel_hi:[0,0,0]
	v_mfma_scale_f32_16x16x128_f8f6f4 v[0:3], v[150:157], v[182:189], v[250:253], v140, v140 op_sel_hi:[0,0,0]
	s_barrier
	s_setprio 0
	s_add_i32 s61, s61, 2
	s_add_u32 s59, s59, 0x100
	s_addc_u32 s60, s60, 0
	s_cmp_gt_u32 s61, 13
	s_mov_b64 s[28:29], s[30:31]
	s_cbranch_scc0 .LBB0_542
	s_and_b64 vcc, exec, s[6:7]
	s_cbranch_vccz .LBB0_545
	s_barrier

; #define PG8_WAIT_V(n) asm volatile("s_waitcnt vmcnt(" #n ")" ::: "memory")
; #define PG8_WAIT_L(n) asm volatile("s_waitcnt lgkmcnt(" #n ")" ::: "memory")
; #define PG8_BAR __builtin_amdgcn_s_barrier()
; #define PG8_SCHED __builtin_amdgcn_sched_barrier(0)
;     ...
;             PG8_LDB(B0, 0, 0); PG8_LDB(B1, 0, 1); PG8_SCHED; PG8_LDA(At, 0, 0); PG8_STAGE(PG8_SA(1, 1), a1 + hstepA, voffA);
;             PG8_WAIT_V(8); PG8_WAIT_L(0); PG8_BAR; PG8_MMA(0, 0, At, B0); PG8_MMA(0, 1, At, B1); PG8_BAR; PG8_SCHED;
;             if constexpr (!HALFU) PG8_LDA(At, 0, 1); PG8_STAGE(PG8_SB(0, 0), b2, voffB); PG8_STAGE(PG8_SB(0, 1), b2 + hstep, voffB); PG8_STAGE(PG8_SA(0, 0), a2, voffA);
;             PG8_WAIT_V(8); PG8_WAIT_L(0); PG8_BAR; if constexpr (!HALFU) { PG8_MMA(1, 0, At, B0); PG8_MMA(1, 1, At, B1); } PG8_BAR; PG8_SCHED;
.LBB0_670:
	s_add_u32 s98, s18, 0x80
	s_addc_u32 s99, s19, 0
	s_mov_b32 m0, s43
	s_nop 0
	global_load_lds_dwordx4 v134, s[98:99]
	s_mov_b32 m0, s44
	s_nop 0
	global_load_lds_dwordx4 v132, s[98:99]
	ds_read_b128 v[144:147], v141
	ds_read_b128 v[148:151], v141 offset:1024
	ds_read_b128 v[152:155], v141 offset:2048
	ds_read_b128 v[156:159], v141 offset:3072
	ds_read_b128 v[160:163], v142
	ds_read_b128 v[164:167], v142 offset:1024
	ds_read_b128 v[168:171], v142 offset:2048
	ds_read_b128 v[172:175], v142 offset:3072
	s_add_u32 s20, s18, 0x100
	s_addc_u32 s21, s19, 0
	s_cmp_eq_u32 s53, 60
	s_cselect_b32 s26, s49, s20
	s_cselect_b32 s27, s11, s21
	s_cselect_b32 s24, s50, s51
	s_cselect_b32 s25, s9, s52
	s_add_u32 s22, s26, 0x80
	s_addc_u32 s23, s27, 0
	s_add_u32 s18, s18, 0x100080
	s_addc_u32 s19, s19, 0
	s_add_i32 m0, s17, 0xc000
	ds_read_b128 v[176:179], v143
	ds_read_b128 v[180:183], v143 offset:1024
	ds_read_b128 v[184:187], v143 offset:2048
	ds_read_b128 v[188:191], v143 offset:3072
	ds_read_b128 v[192:195], v143 offset:4096
	ds_read_b128 v[196:199], v143 offset:5120
	ds_read_b128 v[200:203], v143 offset:6144
	ds_read_b128 v[204:207], v143 offset:7168
	global_load_lds_dwordx4 v134, s[18:19]
	s_add_i32 m0, s17, 0xe000
	s_nop 0
	global_load_lds_dwordx4 v132, s[18:19]
	s_waitcnt vmcnt(8)
	s_waitcnt lgkmcnt(0)
	s_setprio 1
	s_barrier
	v_mfma_f32_16x16x32_bf16 v[124:127], v[144:147], v[176:179], v[124:127]
	v_mfma_f32_16x16x32_bf16 v[120:123], v[152:155], v[176:179], v[120:123]
	v_mfma_f32_16x16x32_bf16 v[108:111], v[144:147], v[184:187], v[108:111]
	v_mfma_f32_16x16x32_bf16 v[104:107], v[152:155], v[184:187], v[104:107]
	v_mfma_f32_16x16x32_bf16 v[92:95], v[144:147], v[192:195], v[92:95]
	v_mfma_f32_16x16x32_bf16 v[88:91], v[152:155], v[192:195], v[88:91]
	v_mfma_f32_16x16x32_bf16 v[76:79], v[144:147], v[200:203], v[76:79]
	v_mfma_f32_16x16x32_bf16 v[72:75], v[152:155], v[200:203], v[72:75]
	v_mfma_f32_16x16x32_bf16 v[124:127], v[148:151], v[180:183], v[124:127]
	v_mfma_f32_16x16x32_bf16 v[120:123], v[156:159], v[180:183], v[120:123]
	v_mfma_f32_16x16x32_bf16 v[108:111], v[148:151], v[188:191], v[108:111]
	v_mfma_f32_16x16x32_bf16 v[104:107], v[156:159], v[188:191], v[104:107]
	v_mfma_f32_16x16x32_bf16 v[92:95], v[148:151], v[196:199], v[92:95]
	v_mfma_f32_16x16x32_bf16 v[88:91], v[156:159], v[196:199], v[88:91]
	v_mfma_f32_16x16x32_bf16 v[76:79], v[148:151], v[204:207], v[76:79]
	v_mfma_f32_16x16x32_bf16 v[72:75], v[156:159], v[204:207], v[72:75]
	v_mfma_f32_16x16x32_bf16 v[116:119], v[160:163], v[176:179], v[116:119]
	v_mfma_f32_16x16x32_bf16 v[112:115], v[168:171], v[176:179], v[112:115]
	v_mfma_f32_16x16x32_bf16 v[100:103], v[160:163], v[184:187], v[100:103]
	v_mfma_f32_16x16x32_bf16 v[96:99], v[168:171], v[184:187], v[96:99]
	v_mfma_f32_16x16x32_bf16 v[84:87], v[160:163], v[192:195], v[84:87]
	v_mfma_f32_16x16x32_bf16 v[80:83], v[168:171], v[192:195], v[80:83]
	v_mfma_f32_16x16x32_bf16 v[68:71], v[160:163], v[200:203], v[68:71]
	v_mfma_f32_16x16x32_bf16 v[64:67], v[168:171], v[200:203], v[64:67]
	v_mfma_f32_16x16x32_bf16 v[116:119], v[164:167], v[180:183], v[116:119]
	v_mfma_f32_16x16x32_bf16 v[112:115], v[172:175], v[180:183], v[112:115]
	v_mfma_f32_16x16x32_bf16 v[100:103], v[164:167], v[188:191], v[100:103]
	v_mfma_f32_16x16x32_bf16 v[96:99], v[172:175], v[188:191], v[96:99]
	v_mfma_f32_16x16x32_bf16 v[84:87], v[164:167], v[196:199], v[84:87]
	v_mfma_f32_16x16x32_bf16 v[80:83], v[172:175], v[196:199], v[80:83]
	v_mfma_f32_16x16x32_bf16 v[68:71], v[164:167], v[204:207], v[68:71]
	v_mfma_f32_16x16x32_bf16 v[64:67], v[172:175], v[204:207], v[64:67]
	s_barrier
	s_setprio 0
	s_add_i32 s18, s45, s30
	s_mov_b32 m0, s18
	ds_read_b128 v[176:179], v143 offset:16384
	ds_read_b128 v[180:183], v143 offset:17408
	ds_read_b128 v[184:187], v143 offset:18432
	ds_read_b128 v[188:191], v143 offset:19456
	ds_read_b128 v[192:195], v143 offset:20480
	ds_read_b128 v[196:199], v143 offset:21504
	ds_read_b128 v[200:203], v143 offset:22528
	ds_read_b128 v[204:207], v143 offset:23552
	global_load_lds_dwordx4 v128, s[24:25]
	s_add_i32 m0, s18, 0x2000
	s_add_u32 s18, s24, 0x100000
	s_addc_u32 s19, s25, 0
	s_add_i32 s54, s46, s30
	global_load_lds_dwordx4 v130, s[24:25]
	s_mov_b32 m0, s54
	s_nop 0
	global_load_lds_dwordx4 v128, s[18:19]
	s_add_i32 m0, s54, 0x2000
	s_nop 0
	global_load_lds_dwordx4 v130, s[18:19]
	s_waitcnt vmcnt(4)
	s_waitcnt lgkmcnt(0)
	s_setprio 1
	s_barrier
	v_mfma_f32_16x16x32_bf16 v[60:63], v[144:147], v[176:179], v[60:63]
	v_mfma_f32_16x16x32_bf16 v[56:59], v[152:155], v[176:179], v[56:59]
	v_mfma_f32_16x16x32_bf16 v[44:47], v[144:147], v[184:187], v[44:47]
	v_mfma_f32_16x16x32_bf16 v[40:43], v[152:155], v[184:187], v[40:43]
	v_mfma_f32_16x16x32_bf16 v[28:31], v[144:147], v[192:195], v[28:31]
	v_mfma_f32_16x16x32_bf16 v[24:27], v[152:155], v[192:195], v[24:27]
	v_mfma_f32_16x16x32_bf16 v[12:15], v[144:147], v[200:203], v[12:15]
	v_mfma_f32_16x16x32_bf16 v[8:11], v[152:155], v[200:203], v[8:11]
	v_mfma_f32_16x16x32_bf16 v[60:63], v[148:151], v[180:183], v[60:63]
	v_mfma_f32_16x16x32_bf16 v[56:59], v[156:159], v[180:183], v[56:59]
	v_mfma_f32_16x16x32_bf16 v[44:47], v[148:151], v[188:191], v[44:47]
	v_mfma_f32_16x16x32_bf16 v[40:43], v[156:159], v[188:191], v[40:43]
	v_mfma_f32_16x16x32_bf16 v[28:31], v[148:151], v[196:199], v[28:31]
	v_mfma_f32_16x16x32_bf16 v[24:27], v[156:159], v[196:199], v[24:27]
	v_mfma_f32_16x16x32_bf16 v[12:15], v[148:151], v[204:207], v[12:15]
	v_mfma_f32_16x16x32_bf16 v[8:11], v[156:159], v[204:207], v[8:11]
	v_mfma_f32_16x16x32_bf16 v[52:55], v[160:163], v[176:179], v[52:55]
	v_mfma_f32_16x16x32_bf16 v[48:51], v[168:171], v[176:179], v[48:51]
	v_mfma_f32_16x16x32_bf16 v[36:39], v[160:163], v[184:187], v[36:39]
	v_mfma_f32_16x16x32_bf16 v[32:35], v[168:171], v[184:187], v[32:35]
	v_mfma_f32_16x16x32_bf16 v[20:23], v[160:163], v[192:195], v[20:23]
	v_mfma_f32_16x16x32_bf16 v[16:19], v[168:171], v[192:195], v[16:19]
	v_mfma_f32_16x16x32_bf16 v[4:7], v[160:163], v[200:203], v[4:7]
	v_mfma_f32_16x16x32_bf16 v[0:3], v[168:171], v[200:203], v[0:3]
	v_mfma_f32_16x16x32_bf16 v[52:55], v[164:167], v[180:183], v[52:55]
	v_mfma_f32_16x16x32_bf16 v[48:51], v[172:175], v[180:183], v[48:51]
	v_mfma_f32_16x16x32_bf16 v[36:39], v[164:167], v[188:191], v[36:39]
	v_mfma_f32_16x16x32_bf16 v[32:35], v[172:175], v[188:191], v[32:35]
	v_mfma_f32_16x16x32_bf16 v[20:23], v[164:167], v[196:199], v[20:23]
	v_mfma_f32_16x16x32_bf16 v[16:19], v[172:175], v[196:199], v[16:19]
	v_mfma_f32_16x16x32_bf16 v[4:7], v[164:167], v[204:207], v[4:7]
	v_mfma_f32_16x16x32_bf16 v[0:3], v[172:175], v[204:207], v[0:3]
	s_barrier
; #define PG8_WAIT_V(n) asm volatile("s_waitcnt vmcnt(" #n ")" ::: "memory")
; #define PG8_WAIT_L(n) asm volatile("s_waitcnt lgkmcnt(" #n ")" ::: "memory")
; #define PG8_BAR __builtin_amdgcn_s_barrier()
; #define PG8_SCHED __builtin_amdgcn_sched_barrier(0)
;     ...
;         for (int t = 0; t < nt; t += 2) {
;             const bool last = (t == nt - 2);
;             const char* a1 = cA + (size_t)(t + 1) * kstep;
;             const char* a2 = last ? nA : cA + (size_t)(t + 2) * kstep; const char* b2 = last ? nB : cB + (size_t)(t + 2) * kstep;
;             const char* a3 = a2 + kstep; const char* b3 = b2 + kstep;
;             if (last && has_next) S.a_ready(nxt);
;     ...
;             PG8_LDB(B0, 1, 0); PG8_LDB(B1, 1, 1); PG8_SCHED; PG8_LDA(At, 1, 0); PG8_STAGE(PG8_SA(0, 1), a2 + hstepA, voffA);
;             PG8_WAIT_V(8); PG8_WAIT_L(0); PG8_BAR; PG8_MMA(0, 0, At, B0); PG8_MMA(0, 1, At, B1); PG8_BAR; PG8_SCHED;
;             if constexpr (!HALFU) PG8_LDA(At, 1, 1); PG8_STAGE(PG8_SB(1, 0), b3, voffB); PG8_STAGE(PG8_SB(1, 1), b3 + hstep, voffB); PG8_STAGE(PG8_SA(1, 0), a3, voffA);
;             PG8_WAIT_V(8); PG8_WAIT_L(0); PG8_BAR; if constexpr (!HALFU) { PG8_MMA(1, 0, At, B0); PG8_MMA(1, 1, At, B1); } PG8_BAR; PG8_SCHED;
	s_setprio 0
	s_mov_b32 m0, s17
	s_nop 0
	global_load_lds_dwordx4 v134, s[26:27]
	s_mov_b32 m0, s36
	s_nop 0
	global_load_lds_dwordx4 v132, s[26:27]
	s_add_i32 s54, 0, 0x18000
	s_add_i32 s55, 0, 0x1c000
	v_add_u32_e32 v156, s54, v140
	v_add_u32_e32 v172, s55, v140
	ds_read_b128 v[144:147], v156
	ds_read_b128 v[148:151], v156 offset:1024
	ds_read_b128 v[152:155], v156 offset:2048
	ds_read_b128 v[156:159], v156 offset:3072
	ds_read_b128 v[160:163], v172
	ds_read_b128 v[164:167], v172 offset:1024
	ds_read_b128 v[168:171], v172 offset:2048
	ds_read_b128 v[172:175], v172 offset:3072
	s_add_u32 s18, s26, 0x100000
	s_addc_u32 s19, s27, 0
	s_mov_b32 m0, s37
	ds_read_b128 v[176:179], v143 offset:32768
	ds_read_b128 v[180:183], v143 offset:33792
	ds_read_b128 v[184:187], v143 offset:34816
	ds_read_b128 v[188:191], v143 offset:35840
	ds_read_b128 v[192:195], v143 offset:36864
	ds_read_b128 v[196:199], v143 offset:37888
	ds_read_b128 v[200:203], v143 offset:38912
	ds_read_b128 v[204:207], v143 offset:39936
	global_load_lds_dwordx4 v134, s[18:19]
	s_mov_b32 m0, s38
	s_nop 0
	global_load_lds_dwordx4 v132, s[18:19]
	s_waitcnt vmcnt(8)
	s_waitcnt lgkmcnt(0)
	s_setprio 1
	s_barrier
	v_mfma_f32_16x16x32_bf16 v[124:127], v[144:147], v[176:179], v[124:127]
	v_mfma_f32_16x16x32_bf16 v[120:123], v[152:155], v[176:179], v[120:123]
	v_mfma_f32_16x16x32_bf16 v[108:111], v[144:147], v[184:187], v[108:111]
	v_mfma_f32_16x16x32_bf16 v[104:107], v[152:155], v[184:187], v[104:107]
	v_mfma_f32_16x16x32_bf16 v[92:95], v[144:147], v[192:195], v[92:95]
	v_mfma_f32_16x16x32_bf16 v[88:91], v[152:155], v[192:195], v[88:91]
	v_mfma_f32_16x16x32_bf16 v[76:79], v[144:147], v[200:203], v[76:79]
	v_mfma_f32_16x16x32_bf16 v[72:75], v[152:155], v[200:203], v[72:75]
	v_mfma_f32_16x16x32_bf16 v[124:127], v[148:151], v[180:183], v[124:127]
	v_mfma_f32_16x16x32_bf16 v[120:123], v[156:159], v[180:183], v[120:123]
	v_mfma_f32_16x16x32_bf16 v[108:111], v[148:151], v[188:191], v[108:111]
	v_mfma_f32_16x16x32_bf16 v[104:107], v[156:159], v[188:191], v[104:107]
	v_mfma_f32_16x16x32_bf16 v[92:95], v[148:151], v[196:199], v[92:95]
	v_mfma_f32_16x16x32_bf16 v[88:91], v[156:159], v[196:199], v[88:91]
	v_mfma_f32_16x16x32_bf16 v[76:79], v[148:151], v[204:207], v[76:79]
	v_mfma_f32_16x16x32_bf16 v[72:75], v[156:159], v[204:207], v[72:75]
	v_mfma_f32_16x16x32_bf16 v[116:119], v[160:163], v[176:179], v[116:119]
	v_mfma_f32_16x16x32_bf16 v[112:115], v[168:171], v[176:179], v[112:115]
	v_mfma_f32_16x16x32_bf16 v[100:103], v[160:163], v[184:187], v[100:103]
	v_mfma_f32_16x16x32_bf16 v[96:99], v[168:171], v[184:187], v[96:99]
	v_mfma_f32_16x16x32_bf16 v[84:87], v[160:163], v[192:195], v[84:87]
	v_mfma_f32_16x16x32_bf16 v[80:83], v[168:171], v[192:195], v[80:83]
	v_mfma_f32_16x16x32_bf16 v[68:71], v[160:163], v[200:203], v[68:71]
	v_mfma_f32_16x16x32_bf16 v[64:67], v[168:171], v[200:203], v[64:67]
	v_mfma_f32_16x16x32_bf16 v[116:119], v[164:167], v[180:183], v[116:119]
	v_mfma_f32_16x16x32_bf16 v[112:115], v[172:175], v[180:183], v[112:115]
	v_mfma_f32_16x16x32_bf16 v[100:103], v[164:167], v[188:191], v[100:103]
	v_mfma_f32_16x16x32_bf16 v[96:99], v[172:175], v[188:191], v[96:99]
	v_mfma_f32_16x16x32_bf16 v[84:87], v[164:167], v[196:199], v[84:87]
	v_mfma_f32_16x16x32_bf16 v[80:83], v[172:175], v[196:199], v[80:83]
	v_mfma_f32_16x16x32_bf16 v[68:71], v[164:167], v[204:207], v[68:71]
	v_mfma_f32_16x16x32_bf16 v[64:67], v[172:175], v[204:207], v[64:67]
	s_barrier
	s_setprio 0
	s_add_u32 s18, s24, 0x80
	s_addc_u32 s19, s25, 0
	s_add_i32 s26, s54, s30
	s_mov_b32 m0, s26
	ds_read_b128 v[176:179], v143 offset:49152
	ds_read_b128 v[180:183], v143 offset:50176
	ds_read_b128 v[184:187], v143 offset:51200
	ds_read_b128 v[188:191], v143 offset:52224
	ds_read_b128 v[192:195], v143 offset:53248
	ds_read_b128 v[196:199], v143 offset:54272
	ds_read_b128 v[200:203], v143 offset:55296
	ds_read_b128 v[204:207], v143 offset:56320
	global_load_lds_dwordx4 v128, s[18:19]
	s_add_i32 m0, s26, 0x2000
	v_lshl_add_u64 v[208:209], s[18:19], 0, v[130:131]
	s_add_u32 s18, s24, 0x100080
	s_addc_u32 s19, s25, 0
	s_add_i32 s24, s55, s30
	global_load_lds_dwordx4 v[208:209], off
	s_mov_b32 m0, s24
	s_nop 0
	global_load_lds_dwordx4 v128, s[18:19]
	s_add_i32 m0, s24, 0x2000
	s_nop 0
	global_load_lds_dwordx4 v130, s[18:19]
	s_waitcnt vmcnt(4)
	s_waitcnt lgkmcnt(0)
	s_setprio 1
	s_barrier
	v_mfma_f32_16x16x32_bf16 v[60:63], v[144:147], v[176:179], v[60:63]
	v_mfma_f32_16x16x32_bf16 v[56:59], v[152:155], v[176:179], v[56:59]
	v_mfma_f32_16x16x32_bf16 v[44:47], v[144:147], v[184:187], v[44:47]
	v_mfma_f32_16x16x32_bf16 v[40:43], v[152:155], v[184:187], v[40:43]
	v_mfma_f32_16x16x32_bf16 v[28:31], v[144:147], v[192:195], v[28:31]
	v_mfma_f32_16x16x32_bf16 v[24:27], v[152:155], v[192:195], v[24:27]
	v_mfma_f32_16x16x32_bf16 v[12:15], v[144:147], v[200:203], v[12:15]
	v_mfma_f32_16x16x32_bf16 v[8:11], v[152:155], v[200:203], v[8:11]
	v_mfma_f32_16x16x32_bf16 v[60:63], v[148:151], v[180:183], v[60:63]
	v_mfma_f32_16x16x32_bf16 v[56:59], v[156:159], v[180:183], v[56:59]
	v_mfma_f32_16x16x32_bf16 v[44:47], v[148:151], v[188:191], v[44:47]
	v_mfma_f32_16x16x32_bf16 v[40:43], v[156:159], v[188:191], v[40:43]
	v_mfma_f32_16x16x32_bf16 v[28:31], v[148:151], v[196:199], v[28:31]
	v_mfma_f32_16x16x32_bf16 v[24:27], v[156:159], v[196:199], v[24:27]
	v_mfma_f32_16x16x32_bf16 v[12:15], v[148:151], v[204:207], v[12:15]
	v_mfma_f32_16x16x32_bf16 v[8:11], v[156:159], v[204:207], v[8:11]
	v_mfma_f32_16x16x32_bf16 v[52:55], v[160:163], v[176:179], v[52:55]
	v_mfma_f32_16x16x32_bf16 v[48:51], v[168:171], v[176:179], v[48:51]
	v_mfma_f32_16x16x32_bf16 v[36:39], v[160:163], v[184:187], v[36:39]
	v_mfma_f32_16x16x32_bf16 v[32:35], v[168:171], v[184:187], v[32:35]
	v_mfma_f32_16x16x32_bf16 v[20:23], v[160:163], v[192:195], v[20:23]
	v_mfma_f32_16x16x32_bf16 v[16:19], v[168:171], v[192:195], v[16:19]
	v_mfma_f32_16x16x32_bf16 v[4:7], v[160:163], v[200:203], v[4:7]
	v_mfma_f32_16x16x32_bf16 v[0:3], v[168:171], v[200:203], v[0:3]
	v_mfma_f32_16x16x32_bf16 v[52:55], v[164:167], v[180:183], v[52:55]
	v_mfma_f32_16x16x32_bf16 v[48:51], v[172:175], v[180:183], v[48:51]
	v_mfma_f32_16x16x32_bf16 v[36:39], v[164:167], v[188:191], v[36:39]
	v_mfma_f32_16x16x32_bf16 v[32:35], v[172:175], v[188:191], v[32:35]
	v_mfma_f32_16x16x32_bf16 v[20:23], v[164:167], v[196:199], v[20:23]
	v_mfma_f32_16x16x32_bf16 v[16:19], v[172:175], v[196:199], v[16:19]
	v_mfma_f32_16x16x32_bf16 v[4:7], v[164:167], v[204:207], v[4:7]
	v_mfma_f32_16x16x32_bf16 v[0:3], v[172:175], v[204:207], v[0:3]
	s_barrier
	s_setprio 0
	s_add_i32 s53, s53, 2
	s_add_u32 s51, s51, 0x100
	s_addc_u32 s52, s52, 0
	s_cmp_gt_u32 s53, 61
	s_mov_b64 s[18:19], s[20:21]
	s_cbranch_scc0 .LBB0_670
	s_and_b64 vcc, exec, s[6:7]
	s_cbranch_vccz .LBB0_673
	s_barrier

; #define PG8_WAIT_V(n) asm volatile("s_waitcnt vmcnt(" #n ")" ::: "memory")
; #define PG8_WAIT_L(n) asm volatile("s_waitcnt lgkmcnt(" #n ")" ::: "memory")
; #define PG8_BAR __builtin_amdgcn_s_barrier()
; #define PG8_SCHED __builtin_amdgcn_sched_barrier(0)
;     ...
;             PG8_LDB(B0, 0, 0); PG8_LDB(B1, 0, 1); PG8_SCHED; PG8_LDA(At, 0, 0); PG8_STAGE(PG8_SA(1, 1), a1 + hstepA, voffA);
;             PG8_WAIT_V(8); PG8_WAIT_L(0); PG8_BAR; PG8_MMA(0, 0, At, B0); PG8_MMA(0, 1, At, B1); PG8_BAR; PG8_SCHED;
;             if constexpr (!HALFU) PG8_LDA(At, 0, 1); PG8_STAGE(PG8_SB(0, 0), b2, voffB); PG8_STAGE(PG8_SB(0, 1), b2 + hstep, voffB); PG8_STAGE(PG8_SA(0, 0), a2, voffA);
;             PG8_WAIT_V(8); PG8_WAIT_L(0); PG8_BAR; if constexpr (!HALFU) { PG8_MMA(1, 0, At, B0); PG8_MMA(1, 1, At, B1); } PG8_BAR; PG8_SCHED;
.LBB0_793:
	s_add_u32 s98, s10, 0x80
	s_addc_u32 s99, s11, 0
	s_mov_b32 m0, s43
	s_nop 0
	global_load_lds_dwordx4 v128, s[98:99]
	s_mov_b32 m0, s44
	s_nop 0
	global_load_lds_dwordx4 v130, s[98:99]
	ds_read_b128 v[140:143], v137
	ds_read_b128 v[144:147], v137 offset:1024
	ds_read_b128 v[148:151], v137 offset:2048
	ds_read_b128 v[152:155], v137 offset:3072
	ds_read_b128 v[156:159], v138
	ds_read_b128 v[160:163], v138 offset:1024
	ds_read_b128 v[164:167], v138 offset:2048
	ds_read_b128 v[168:171], v138 offset:3072
	s_add_u32 s22, s10, 0x100
	s_addc_u32 s23, s11, 0
	s_cmpk_eq_i32 s54, 0xa8
	s_cselect_b32 s28, s6, s22
	s_cselect_b32 s29, s7, s23
	s_cselect_b32 s26, s20, s52
	s_cselect_b32 s27, s21, s53
	s_add_u32 s24, s28, 0x80
	s_addc_u32 s25, s29, 0
	s_add_u32 s10, s10, 0x2b0080
	s_addc_u32 s11, s11, 0
	s_add_i32 m0, s36, 0xc000
	ds_read_b128 v[172:175], v139
	ds_read_b128 v[176:179], v139 offset:1024
	ds_read_b128 v[180:183], v139 offset:2048
	ds_read_b128 v[184:187], v139 offset:3072
	ds_read_b128 v[188:191], v139 offset:4096
	ds_read_b128 v[192:195], v139 offset:5120
	ds_read_b128 v[196:199], v139 offset:6144
	ds_read_b128 v[200:203], v139 offset:7168
	global_load_lds_dwordx4 v128, s[10:11]
	s_add_i32 m0, s36, 0xe000
	s_nop 0
	global_load_lds_dwordx4 v130, s[10:11]
	s_waitcnt vmcnt(8)
	s_waitcnt lgkmcnt(0)
	s_setprio 1
	s_barrier
	v_mfma_f32_16x16x32_bf16 v[124:127], v[140:143], v[172:175], v[124:127]
	v_mfma_f32_16x16x32_bf16 v[120:123], v[148:151], v[172:175], v[120:123]
	v_mfma_f32_16x16x32_bf16 v[112:115], v[140:143], v[180:183], v[112:115]
	v_mfma_f32_16x16x32_bf16 v[104:107], v[148:151], v[180:183], v[104:107]
	v_mfma_f32_16x16x32_bf16 v[96:99], v[140:143], v[188:191], v[96:99]
	v_mfma_f32_16x16x32_bf16 v[88:91], v[148:151], v[188:191], v[88:91]
	v_mfma_f32_16x16x32_bf16 v[80:83], v[140:143], v[196:199], v[80:83]
	v_mfma_f32_16x16x32_bf16 v[72:75], v[148:151], v[196:199], v[72:75]
	v_mfma_f32_16x16x32_bf16 v[124:127], v[144:147], v[176:179], v[124:127]
	v_mfma_f32_16x16x32_bf16 v[120:123], v[152:155], v[176:179], v[120:123]
	v_mfma_f32_16x16x32_bf16 v[112:115], v[144:147], v[184:187], v[112:115]
	v_mfma_f32_16x16x32_bf16 v[104:107], v[152:155], v[184:187], v[104:107]
	v_mfma_f32_16x16x32_bf16 v[96:99], v[144:147], v[192:195], v[96:99]
	v_mfma_f32_16x16x32_bf16 v[88:91], v[152:155], v[192:195], v[88:91]
	v_mfma_f32_16x16x32_bf16 v[80:83], v[144:147], v[200:203], v[80:83]
	v_mfma_f32_16x16x32_bf16 v[72:75], v[152:155], v[200:203], v[72:75]
	v_mfma_f32_16x16x32_bf16 v[116:119], v[156:159], v[172:175], v[116:119]
	v_mfma_f32_16x16x32_bf16 v[108:111], v[164:167], v[172:175], v[108:111]
	v_mfma_f32_16x16x32_bf16 v[100:103], v[156:159], v[180:183], v[100:103]
	v_mfma_f32_16x16x32_bf16 v[92:95], v[164:167], v[180:183], v[92:95]
	v_mfma_f32_16x16x32_bf16 v[84:87], v[156:159], v[188:191], v[84:87]
	v_mfma_f32_16x16x32_bf16 v[76:79], v[164:167], v[188:191], v[76:79]
	v_mfma_f32_16x16x32_bf16 v[68:71], v[156:159], v[196:199], v[68:71]
	v_mfma_f32_16x16x32_bf16 v[64:67], v[164:167], v[196:199], v[64:67]
	v_mfma_f32_16x16x32_bf16 v[116:119], v[160:163], v[176:179], v[116:119]
	v_mfma_f32_16x16x32_bf16 v[108:111], v[168:171], v[176:179], v[108:111]
	v_mfma_f32_16x16x32_bf16 v[100:103], v[160:163], v[184:187], v[100:103]
	v_mfma_f32_16x16x32_bf16 v[92:95], v[168:171], v[184:187], v[92:95]
	v_mfma_f32_16x16x32_bf16 v[84:87], v[160:163], v[192:195], v[84:87]
	v_mfma_f32_16x16x32_bf16 v[76:79], v[168:171], v[192:195], v[76:79]
	v_mfma_f32_16x16x32_bf16 v[68:71], v[160:163], v[200:203], v[68:71]
	v_mfma_f32_16x16x32_bf16 v[64:67], v[168:171], v[200:203], v[64:67]
	s_barrier
	s_setprio 0
	s_add_i32 s10, s46, s31
	s_mov_b32 m0, s10
	ds_read_b128 v[172:175], v139 offset:16384
	ds_read_b128 v[176:179], v139 offset:17408
	ds_read_b128 v[180:183], v139 offset:18432
	ds_read_b128 v[184:187], v139 offset:19456
	ds_read_b128 v[188:191], v139 offset:20480
	ds_read_b128 v[192:195], v139 offset:21504
	ds_read_b128 v[196:199], v139 offset:22528
	ds_read_b128 v[200:203], v139 offset:23552
	global_load_lds_dwordx4 v128, s[26:27]
	s_add_i32 m0, s10, 0x2000
	s_add_u32 s10, s26, 0x2b0000
	s_addc_u32 s11, s27, 0
	s_add_i32 s55, s47, s31
	global_load_lds_dwordx4 v130, s[26:27]
	s_mov_b32 m0, s55
	s_nop 0
	global_load_lds_dwordx4 v128, s[10:11]
	s_add_i32 m0, s55, 0x2000
	s_nop 0
	global_load_lds_dwordx4 v130, s[10:11]
	s_waitcnt vmcnt(4)
	s_waitcnt lgkmcnt(0)
	s_setprio 1
	s_barrier
	v_mfma_f32_16x16x32_bf16 v[60:63], v[140:143], v[172:175], v[60:63]
	v_mfma_f32_16x16x32_bf16 v[56:59], v[148:151], v[172:175], v[56:59]
	v_mfma_f32_16x16x32_bf16 v[48:51], v[140:143], v[180:183], v[48:51]
	v_mfma_f32_16x16x32_bf16 v[40:43], v[148:151], v[180:183], v[40:43]
	v_mfma_f32_16x16x32_bf16 v[32:35], v[140:143], v[188:191], v[32:35]
	v_mfma_f32_16x16x32_bf16 v[24:27], v[148:151], v[188:191], v[24:27]
	v_mfma_f32_16x16x32_bf16 v[16:19], v[140:143], v[196:199], v[16:19]
	v_mfma_f32_16x16x32_bf16 v[8:11], v[148:151], v[196:199], v[8:11]
	v_mfma_f32_16x16x32_bf16 v[60:63], v[144:147], v[176:179], v[60:63]
	v_mfma_f32_16x16x32_bf16 v[56:59], v[152:155], v[176:179], v[56:59]
	v_mfma_f32_16x16x32_bf16 v[48:51], v[144:147], v[184:187], v[48:51]
	v_mfma_f32_16x16x32_bf16 v[40:43], v[152:155], v[184:187], v[40:43]
	v_mfma_f32_16x16x32_bf16 v[32:35], v[144:147], v[192:195], v[32:35]
	v_mfma_f32_16x16x32_bf16 v[24:27], v[152:155], v[192:195], v[24:27]
	v_mfma_f32_16x16x32_bf16 v[16:19], v[144:147], v[200:203], v[16:19]
	v_mfma_f32_16x16x32_bf16 v[8:11], v[152:155], v[200:203], v[8:11]
	v_mfma_f32_16x16x32_bf16 v[52:55], v[156:159], v[172:175], v[52:55]
	v_mfma_f32_16x16x32_bf16 v[44:47], v[164:167], v[172:175], v[44:47]
	v_mfma_f32_16x16x32_bf16 v[36:39], v[156:159], v[180:183], v[36:39]
	v_mfma_f32_16x16x32_bf16 v[28:31], v[164:167], v[180:183], v[28:31]
	v_mfma_f32_16x16x32_bf16 v[20:23], v[156:159], v[188:191], v[20:23]
	v_mfma_f32_16x16x32_bf16 v[12:15], v[164:167], v[188:191], v[12:15]
	v_mfma_f32_16x16x32_bf16 v[4:7], v[156:159], v[196:199], v[4:7]
	v_mfma_f32_16x16x32_bf16 v[0:3], v[164:167], v[196:199], v[0:3]
	v_mfma_f32_16x16x32_bf16 v[52:55], v[160:163], v[176:179], v[52:55]
	v_mfma_f32_16x16x32_bf16 v[44:47], v[168:171], v[176:179], v[44:47]
	v_mfma_f32_16x16x32_bf16 v[36:39], v[160:163], v[184:187], v[36:39]
	v_mfma_f32_16x16x32_bf16 v[28:31], v[168:171], v[184:187], v[28:31]
	v_mfma_f32_16x16x32_bf16 v[20:23], v[160:163], v[192:195], v[20:23]
	v_mfma_f32_16x16x32_bf16 v[12:15], v[168:171], v[192:195], v[12:15]
	v_mfma_f32_16x16x32_bf16 v[4:7], v[160:163], v[200:203], v[4:7]
	v_mfma_f32_16x16x32_bf16 v[0:3], v[168:171], v[200:203], v[0:3]
	s_barrier
; #define PG8_WAIT_V(n) asm volatile("s_waitcnt vmcnt(" #n ")" ::: "memory")
; #define PG8_WAIT_L(n) asm volatile("s_waitcnt lgkmcnt(" #n ")" ::: "memory")
; #define PG8_BAR __builtin_amdgcn_s_barrier()
; #define PG8_SCHED __builtin_amdgcn_sched_barrier(0)
;     ...
;         for (int t = 0; t < nt; t += 2) {
;             const bool last = (t == nt - 2);
;             const char* a1 = cA + (size_t)(t + 1) * kstep;
;             const char* a2 = last ? nA : cA + (size_t)(t + 2) * kstep; const char* b2 = last ? nB : cB + (size_t)(t + 2) * kstep;
;             const char* a3 = a2 + kstep; const char* b3 = b2 + kstep;
;             if (last && has_next) S.a_ready(nxt);
;     ...
;             PG8_LDB(B0, 1, 0); PG8_LDB(B1, 1, 1); PG8_SCHED; PG8_LDA(At, 1, 0); PG8_STAGE(PG8_SA(0, 1), a2 + hstepA, voffA);
;             PG8_WAIT_V(8); PG8_WAIT_L(0); PG8_BAR; PG8_MMA(0, 0, At, B0); PG8_MMA(0, 1, At, B1); PG8_BAR; PG8_SCHED;
;             if constexpr (!HALFU) PG8_LDA(At, 1, 1); PG8_STAGE(PG8_SB(1, 0), b3, voffB); PG8_STAGE(PG8_SB(1, 1), b3 + hstep, voffB); PG8_STAGE(PG8_SA(1, 0), a3, voffA);
;             PG8_WAIT_V(8); PG8_WAIT_L(0); PG8_BAR; if constexpr (!HALFU) { PG8_MMA(1, 0, At, B0); PG8_MMA(1, 1, At, B1); } PG8_BAR; PG8_SCHED;
	s_setprio 0
	s_mov_b32 m0, s36
	s_nop 0
	global_load_lds_dwordx4 v128, s[28:29]
	s_mov_b32 m0, s37
	s_nop 0
	global_load_lds_dwordx4 v130, s[28:29]
	s_add_i32 s55, 0, 0x18000
	s_add_i32 s56, 0, 0x1c000
	v_add_u32_e32 v152, s55, v136
	v_add_u32_e32 v168, s56, v136
	ds_read_b128 v[140:143], v152
	ds_read_b128 v[144:147], v152 offset:1024
	ds_read_b128 v[148:151], v152 offset:2048
	ds_read_b128 v[152:155], v152 offset:3072
	ds_read_b128 v[156:159], v168
	ds_read_b128 v[160:163], v168 offset:1024
	ds_read_b128 v[164:167], v168 offset:2048
	ds_read_b128 v[168:171], v168 offset:3072
	s_add_u32 s10, s28, 0x2b0000
	s_addc_u32 s11, s29, 0
	s_mov_b32 m0, s38
	ds_read_b128 v[172:175], v139 offset:32768
	ds_read_b128 v[176:179], v139 offset:33792
	ds_read_b128 v[180:183], v139 offset:34816
	ds_read_b128 v[184:187], v139 offset:35840
	ds_read_b128 v[188:191], v139 offset:36864
	ds_read_b128 v[192:195], v139 offset:37888
	ds_read_b128 v[196:199], v139 offset:38912
	ds_read_b128 v[200:203], v139 offset:39936
	global_load_lds_dwordx4 v128, s[10:11]
	s_mov_b32 m0, s39
	s_nop 0
	global_load_lds_dwordx4 v130, s[10:11]
	s_waitcnt vmcnt(8)
	s_waitcnt lgkmcnt(0)
	s_setprio 1
	s_barrier
	v_mfma_f32_16x16x32_bf16 v[124:127], v[140:143], v[172:175], v[124:127]
	v_mfma_f32_16x16x32_bf16 v[120:123], v[148:151], v[172:175], v[120:123]
	v_mfma_f32_16x16x32_bf16 v[112:115], v[140:143], v[180:183], v[112:115]
	v_mfma_f32_16x16x32_bf16 v[104:107], v[148:151], v[180:183], v[104:107]
	v_mfma_f32_16x16x32_bf16 v[96:99], v[140:143], v[188:191], v[96:99]
	v_mfma_f32_16x16x32_bf16 v[88:91], v[148:151], v[188:191], v[88:91]
	v_mfma_f32_16x16x32_bf16 v[80:83], v[140:143], v[196:199], v[80:83]
	v_mfma_f32_16x16x32_bf16 v[72:75], v[148:151], v[196:199], v[72:75]
	v_mfma_f32_16x16x32_bf16 v[124:127], v[144:147], v[176:179], v[124:127]
	v_mfma_f32_16x16x32_bf16 v[120:123], v[152:155], v[176:179], v[120:123]
	v_mfma_f32_16x16x32_bf16 v[112:115], v[144:147], v[184:187], v[112:115]
	v_mfma_f32_16x16x32_bf16 v[104:107], v[152:155], v[184:187], v[104:107]
	v_mfma_f32_16x16x32_bf16 v[96:99], v[144:147], v[192:195], v[96:99]
	v_mfma_f32_16x16x32_bf16 v[88:91], v[152:155], v[192:195], v[88:91]
	v_mfma_f32_16x16x32_bf16 v[80:83], v[144:147], v[200:203], v[80:83]
	v_mfma_f32_16x16x32_bf16 v[72:75], v[152:155], v[200:203], v[72:75]
	v_mfma_f32_16x16x32_bf16 v[116:119], v[156:159], v[172:175], v[116:119]
	v_mfma_f32_16x16x32_bf16 v[108:111], v[164:167], v[172:175], v[108:111]
	v_mfma_f32_16x16x32_bf16 v[100:103], v[156:159], v[180:183], v[100:103]
	v_mfma_f32_16x16x32_bf16 v[92:95], v[164:167], v[180:183], v[92:95]
	v_mfma_f32_16x16x32_bf16 v[84:87], v[156:159], v[188:191], v[84:87]
	v_mfma_f32_16x16x32_bf16 v[76:79], v[164:167], v[188:191], v[76:79]
	v_mfma_f32_16x16x32_bf16 v[68:71], v[156:159], v[196:199], v[68:71]
	v_mfma_f32_16x16x32_bf16 v[64:67], v[164:167], v[196:199], v[64:67]
	v_mfma_f32_16x16x32_bf16 v[116:119], v[160:163], v[176:179], v[116:119]
	v_mfma_f32_16x16x32_bf16 v[108:111], v[168:171], v[176:179], v[108:111]
	v_mfma_f32_16x16x32_bf16 v[100:103], v[160:163], v[184:187], v[100:103]
	v_mfma_f32_16x16x32_bf16 v[92:95], v[168:171], v[184:187], v[92:95]
	v_mfma_f32_16x16x32_bf16 v[84:87], v[160:163], v[192:195], v[84:87]
	v_mfma_f32_16x16x32_bf16 v[76:79], v[168:171], v[192:195], v[76:79]
	v_mfma_f32_16x16x32_bf16 v[68:71], v[160:163], v[200:203], v[68:71]
	v_mfma_f32_16x16x32_bf16 v[64:67], v[168:171], v[200:203], v[64:67]
	s_barrier
	s_setprio 0
	s_add_u32 s10, s26, 0x80
	s_addc_u32 s11, s27, 0
	s_add_i32 s28, s55, s31
	s_mov_b32 m0, s28
	ds_read_b128 v[172:175], v139 offset:49152
	ds_read_b128 v[176:179], v139 offset:50176
	ds_read_b128 v[180:183], v139 offset:51200
	ds_read_b128 v[184:187], v139 offset:52224
	ds_read_b128 v[188:191], v139 offset:53248
	ds_read_b128 v[192:195], v139 offset:54272
	ds_read_b128 v[196:199], v139 offset:55296
	ds_read_b128 v[200:203], v139 offset:56320
	global_load_lds_dwordx4 v128, s[10:11]
	s_add_i32 m0, s28, 0x2000
	v_lshl_add_u64 v[204:205], s[10:11], 0, v[130:131]
	s_add_u32 s10, s26, 0x2b0080
	s_addc_u32 s11, s27, 0
	s_add_i32 s26, s56, s31
	global_load_lds_dwordx4 v[204:205], off
	s_mov_b32 m0, s26
	s_nop 0
	global_load_lds_dwordx4 v128, s[10:11]
	s_add_i32 m0, s26, 0x2000
	s_nop 0
	global_load_lds_dwordx4 v130, s[10:11]
	s_waitcnt vmcnt(4)
	s_waitcnt lgkmcnt(0)
	s_setprio 1
	s_barrier
	v_mfma_f32_16x16x32_bf16 v[60:63], v[140:143], v[172:175], v[60:63]
	v_mfma_f32_16x16x32_bf16 v[56:59], v[148:151], v[172:175], v[56:59]
	v_mfma_f32_16x16x32_bf16 v[48:51], v[140:143], v[180:183], v[48:51]
	v_mfma_f32_16x16x32_bf16 v[40:43], v[148:151], v[180:183], v[40:43]
	v_mfma_f32_16x16x32_bf16 v[32:35], v[140:143], v[188:191], v[32:35]
	v_mfma_f32_16x16x32_bf16 v[24:27], v[148:151], v[188:191], v[24:27]
	v_mfma_f32_16x16x32_bf16 v[16:19], v[140:143], v[196:199], v[16:19]
	v_mfma_f32_16x16x32_bf16 v[8:11], v[148:151], v[196:199], v[8:11]
	v_mfma_f32_16x16x32_bf16 v[60:63], v[144:147], v[176:179], v[60:63]
	v_mfma_f32_16x16x32_bf16 v[56:59], v[152:155], v[176:179], v[56:59]
	v_mfma_f32_16x16x32_bf16 v[48:51], v[144:147], v[184:187], v[48:51]
	v_mfma_f32_16x16x32_bf16 v[40:43], v[152:155], v[184:187], v[40:43]
	v_mfma_f32_16x16x32_bf16 v[32:35], v[144:147], v[192:195], v[32:35]
	v_mfma_f32_16x16x32_bf16 v[24:27], v[152:155], v[192:195], v[24:27]
	v_mfma_f32_16x16x32_bf16 v[16:19], v[144:147], v[200:203], v[16:19]
	v_mfma_f32_16x16x32_bf16 v[8:11], v[152:155], v[200:203], v[8:11]
	v_mfma_f32_16x16x32_bf16 v[52:55], v[156:159], v[172:175], v[52:55]
	v_mfma_f32_16x16x32_bf16 v[44:47], v[164:167], v[172:175], v[44:47]
	v_mfma_f32_16x16x32_bf16 v[36:39], v[156:159], v[180:183], v[36:39]
	v_mfma_f32_16x16x32_bf16 v[28:31], v[164:167], v[180:183], v[28:31]
	v_mfma_f32_16x16x32_bf16 v[20:23], v[156:159], v[188:191], v[20:23]
	v_mfma_f32_16x16x32_bf16 v[12:15], v[164:167], v[188:191], v[12:15]
	v_mfma_f32_16x16x32_bf16 v[4:7], v[156:159], v[196:199], v[4:7]
	v_mfma_f32_16x16x32_bf16 v[0:3], v[164:167], v[196:199], v[0:3]
	v_mfma_f32_16x16x32_bf16 v[52:55], v[160:163], v[176:179], v[52:55]
	v_mfma_f32_16x16x32_bf16 v[44:47], v[168:171], v[176:179], v[44:47]
	v_mfma_f32_16x16x32_bf16 v[36:39], v[160:163], v[184:187], v[36:39]
	v_mfma_f32_16x16x32_bf16 v[28:31], v[168:171], v[184:187], v[28:31]
	v_mfma_f32_16x16x32_bf16 v[20:23], v[160:163], v[192:195], v[20:23]
	v_mfma_f32_16x16x32_bf16 v[12:15], v[168:171], v[192:195], v[12:15]
	v_mfma_f32_16x16x32_bf16 v[4:7], v[160:163], v[200:203], v[4:7]
	v_mfma_f32_16x16x32_bf16 v[0:3], v[168:171], v[200:203], v[0:3]
	s_barrier
	s_setprio 0
	s_add_i32 s54, s54, 2
	s_add_u32 s52, s52, 0x100
	s_addc_u32 s53, s53, 0
	s_cmpk_gt_u32 s54, 0xa9
	s_mov_b64 s[10:11], s[22:23]
	s_cbranch_scc0 .LBB0_793
	s_and_b64 vcc, exec, s[12:13]
	s_cbranch_vccz .LBB0_796
	s_barrier

; #define PG8_WAIT_V(n) asm volatile("s_waitcnt vmcnt(" #n ")" ::: "memory")
; #define PG8_WAIT_L(n) asm volatile("s_waitcnt lgkmcnt(" #n ")" ::: "memory")
; #define PG8_BAR __builtin_amdgcn_s_barrier()
; #define PG8_SCHED __builtin_amdgcn_sched_barrier(0)
;     ...
;             PG8_LDB(B0, 0, 0); PG8_LDB(B1, 0, 1); PG8_SCHED; PG8_LDA(At, 0, 0); PG8_STAGE(PG8_SA(1, 1), a1 + hstepA, voffA);
;             PG8_WAIT_V(8); PG8_WAIT_L(0); PG8_BAR; PG8_MMA(0, 0, At, B0); PG8_MMA(0, 1, At, B1); PG8_BAR; PG8_SCHED;
;             if constexpr (!HALFU) PG8_LDA(At, 0, 1); PG8_STAGE(PG8_SB(0, 0), b2, voffB); PG8_STAGE(PG8_SB(0, 1), b2 + hstep, voffB); PG8_STAGE(PG8_SA(0, 0), a2, voffA);
;             PG8_WAIT_V(8); PG8_WAIT_L(0); PG8_BAR; if constexpr (!HALFU) { PG8_MMA(1, 0, At, B0); PG8_MMA(1, 1, At, B1); } PG8_BAR; PG8_SCHED;
.LBB0_1200:
	s_add_u32 s98, s10, 0x80
	s_addc_u32 s99, s11, 0
	s_mov_b32 m0, s68
	s_nop 0
	global_load_lds_dwordx4 v136, s[98:99]
	s_mov_b32 m0, s69
	s_nop 0
	global_load_lds_dwordx4 v140, s[98:99]
	ds_read_b128 v[128:131], v149
	ds_read_b128 v[132:135], v149 offset:1024
	ds_read_b128 v[154:157], v149 offset:2048
	ds_read_b128 v[158:161], v149 offset:3072
	ds_read_b128 v[162:165], v150
	ds_read_b128 v[166:169], v150 offset:1024
	ds_read_b128 v[170:173], v150 offset:2048
	ds_read_b128 v[174:177], v150 offset:3072
	s_add_u32 s26, s10, 0x100
	s_addc_u32 s27, s11, 0
	s_cmp_eq_u32 s76, 28
	s_cselect_b32 s50, s9, s26
	s_cselect_b32 s51, s7, s27
	s_cselect_b32 s48, s43, s74
	s_cselect_b32 s49, s41, s75
	s_add_u32 s30, s50, 0x80
	s_addc_u32 s31, s51, 0
	s_add_u32 s10, s10, 0x80080
	s_addc_u32 s11, s11, 0
	s_add_i32 m0, s57, 0xc000
	ds_read_b128 v[178:181], v151
	ds_read_b128 v[182:185], v151 offset:1024
	ds_read_b128 v[186:189], v151 offset:2048
	ds_read_b128 v[190:193], v151 offset:3072
	ds_read_b128 v[194:197], v151 offset:4096
	ds_read_b128 v[198:201], v151 offset:5120
	ds_read_b128 v[202:205], v151 offset:6144
	ds_read_b128 v[206:209], v151 offset:7168
	global_load_lds_dwordx4 v136, s[10:11]
	s_add_i32 m0, s57, 0xe000
	s_nop 0
	global_load_lds_dwordx4 v140, s[10:11]
	s_waitcnt vmcnt(8)
	s_waitcnt lgkmcnt(0)
	s_setprio 1
	s_barrier
	v_mfma_scale_f32_16x16x128_f8f6f4 v[124:127], v[128:135], v[178:185], v[124:127], v152, v152 op_sel_hi:[0,0,0]
	v_mfma_scale_f32_16x16x128_f8f6f4 v[120:123], v[154:161], v[178:185], v[120:123], v152, v152 op_sel_hi:[0,0,0]
	v_mfma_scale_f32_16x16x128_f8f6f4 v[108:111], v[128:135], v[186:193], v[108:111], v152, v152 op_sel_hi:[0,0,0]
	v_mfma_scale_f32_16x16x128_f8f6f4 v[104:107], v[154:161], v[186:193], v[104:107], v152, v152 op_sel_hi:[0,0,0]
	v_mfma_scale_f32_16x16x128_f8f6f4 v[210:213], v[128:135], v[194:201], v[92:95], v152, v152 op_sel_hi:[0,0,0]
	v_mfma_scale_f32_16x16x128_f8f6f4 v[214:217], v[154:161], v[194:201], v[88:91], v152, v152 op_sel_hi:[0,0,0]
	v_mfma_scale_f32_16x16x128_f8f6f4 v[218:221], v[128:135], v[202:209], v[76:79], v152, v152 op_sel_hi:[0,0,0]
	v_mfma_scale_f32_16x16x128_f8f6f4 v[222:225], v[154:161], v[202:209], v[72:75], v152, v152 op_sel_hi:[0,0,0]
	v_mfma_scale_f32_16x16x128_f8f6f4 v[116:119], v[162:169], v[178:185], v[116:119], v152, v152 op_sel_hi:[0,0,0]
	v_mfma_scale_f32_16x16x128_f8f6f4 v[112:115], v[170:177], v[178:185], v[112:115], v152, v152 op_sel_hi:[0,0,0]
	v_mfma_scale_f32_16x16x128_f8f6f4 v[100:103], v[162:169], v[186:193], v[100:103], v152, v152 op_sel_hi:[0,0,0]
	v_mfma_scale_f32_16x16x128_f8f6f4 v[96:99], v[170:177], v[186:193], v[96:99], v152, v152 op_sel_hi:[0,0,0]
	v_mfma_scale_f32_16x16x128_f8f6f4 v[178:181], v[162:169], v[194:201], v[84:87], v152, v152 op_sel_hi:[0,0,0]
	v_mfma_scale_f32_16x16x128_f8f6f4 v[182:185], v[170:177], v[194:201], v[80:83], v152, v152 op_sel_hi:[0,0,0]
	v_mfma_scale_f32_16x16x128_f8f6f4 v[186:189], v[162:169], v[202:209], v[68:71], v152, v152 op_sel_hi:[0,0,0]
	v_mfma_scale_f32_16x16x128_f8f6f4 v[190:193], v[170:177], v[202:209], v[64:67], v152, v152 op_sel_hi:[0,0,0]
	s_barrier
	s_setprio 0
	s_add_i32 s10, s71, s56
	s_mov_b32 m0, s10
	s_nop 1
	ds_read_b128 v[64:67], v151 offset:16384
	ds_read_b128 v[68:71], v151 offset:17408
	ds_read_b128 v[72:75], v151 offset:18432
	ds_read_b128 v[76:79], v151 offset:19456
	ds_read_b128 v[80:83], v151 offset:20480
	ds_read_b128 v[84:87], v151 offset:21504
	ds_read_b128 v[88:91], v151 offset:22528
	ds_read_b128 v[92:95], v151 offset:23552
	global_load_lds_dwordx4 v138, s[48:49]
	s_add_i32 m0, s10, 0x2000
	s_add_u32 s10, s48, 0x80000
	s_addc_u32 s11, s49, 0
	s_add_i32 s77, s72, s56
	global_load_lds_dwordx4 v142, s[48:49]
	s_mov_b32 m0, s77
	s_nop 0
	global_load_lds_dwordx4 v138, s[10:11]
	s_add_i32 m0, s77, 0x2000
	s_nop 0
	global_load_lds_dwordx4 v142, s[10:11]
	s_waitcnt vmcnt(4)
	s_waitcnt lgkmcnt(0)
	s_setprio 1
	s_barrier
	v_mfma_scale_f32_16x16x128_f8f6f4 v[60:63], v[128:135], v[64:71], v[60:63], v152, v152 op_sel_hi:[0,0,0]
	v_mfma_scale_f32_16x16x128_f8f6f4 v[56:59], v[154:161], v[64:71], v[56:59], v152, v152 op_sel_hi:[0,0,0]
	v_mfma_scale_f32_16x16x128_f8f6f4 v[194:197], v[128:135], v[72:79], v[44:47], v152, v152 op_sel_hi:[0,0,0]
	v_mfma_scale_f32_16x16x128_f8f6f4 v[198:201], v[154:161], v[72:79], v[40:43], v152, v152 op_sel_hi:[0,0,0]
	v_mfma_scale_f32_16x16x128_f8f6f4 v[202:205], v[128:135], v[80:87], v[28:31], v152, v152 op_sel_hi:[0,0,0]
	v_mfma_scale_f32_16x16x128_f8f6f4 v[206:209], v[154:161], v[80:87], v[24:27], v152, v152 op_sel_hi:[0,0,0]
	v_mfma_scale_f32_16x16x128_f8f6f4 v[226:229], v[128:135], v[88:95], v[12:15], v152, v152 op_sel_hi:[0,0,0]
	v_mfma_scale_f32_16x16x128_f8f6f4 v[230:233], v[154:161], v[88:95], v[8:11], v152, v152 op_sel_hi:[0,0,0]
	v_mfma_scale_f32_16x16x128_f8f6f4 v[52:55], v[162:169], v[64:71], v[52:55], v152, v152 op_sel_hi:[0,0,0]
	v_mfma_scale_f32_16x16x128_f8f6f4 v[48:51], v[170:177], v[64:71], v[48:51], v152, v152 op_sel_hi:[0,0,0]
	v_mfma_scale_f32_16x16x128_f8f6f4 v[234:237], v[162:169], v[72:79], v[36:39], v152, v152 op_sel_hi:[0,0,0]
	v_mfma_scale_f32_16x16x128_f8f6f4 v[238:241], v[170:177], v[72:79], v[32:35], v152, v152 op_sel_hi:[0,0,0]
	v_mfma_scale_f32_16x16x128_f8f6f4 v[242:245], v[162:169], v[80:87], v[20:23], v152, v152 op_sel_hi:[0,0,0]
	v_mfma_scale_f32_16x16x128_f8f6f4 v[246:249], v[170:177], v[80:87], v[16:19], v152, v152 op_sel_hi:[0,0,0]
	v_mfma_scale_f32_16x16x128_f8f6f4 v[250:253], v[162:169], v[88:95], v[4:7], v152, v152 op_sel_hi:[0,0,0]
	v_mfma_scale_f32_16x16x128_f8f6f4 v[144:147], v[170:177], v[88:95], v[0:3], v152, v152 op_sel_hi:[0,0,0]
	s_barrier
; #define PG8_WAIT_V(n) asm volatile("s_waitcnt vmcnt(" #n ")" ::: "memory")
; #define PG8_WAIT_L(n) asm volatile("s_waitcnt lgkmcnt(" #n ")" ::: "memory")
; #define PG8_BAR __builtin_amdgcn_s_barrier()
; #define PG8_SCHED __builtin_amdgcn_sched_barrier(0)
;     ...
;         for (int t = 0; t < nt; t += 2) {
;             const bool last = (t == nt - 2);
;             const char* a1 = cA + (size_t)(t + 1) * kstep;
;             const char* a2 = last ? nA : cA + (size_t)(t + 2) * kstep; const char* b2 = last ? nB : cB + (size_t)(t + 2) * kstep;
;             const char* a3 = a2 + kstep; const char* b3 = b2 + kstep;
;             if (last && has_next) S.a_ready(nxt);
;     ...
;             PG8_LDB(B0, 1, 0); PG8_LDB(B1, 1, 1); PG8_SCHED; PG8_LDA(At, 1, 0); PG8_STAGE(PG8_SA(0, 1), a2 + hstepA, voffA);
;             PG8_WAIT_V(8); PG8_WAIT_L(0); PG8_BAR; PG8_MMA(0, 0, At, B0); PG8_MMA(0, 1, At, B1); PG8_BAR; PG8_SCHED;
;             if constexpr (!HALFU) PG8_LDA(At, 1, 1); PG8_STAGE(PG8_SB(1, 0), b3, voffB); PG8_STAGE(PG8_SB(1, 1), b3 + hstep, voffB); PG8_STAGE(PG8_SA(1, 0), a3, voffA);
;             PG8_WAIT_V(8); PG8_WAIT_L(0); PG8_BAR; if constexpr (!HALFU) { PG8_MMA(1, 0, At, B0); PG8_MMA(1, 1, At, B1); } PG8_BAR; PG8_SCHED;
	s_setprio 0
	s_mov_b32 m0, s57
	s_nop 0
	global_load_lds_dwordx4 v136, s[50:51]
	s_mov_b32 m0, s62
	s_nop 0
	global_load_lds_dwordx4 v140, s[50:51]
	s_add_i32 s77, 0, 0x18000
	v_add_u32_e32 v8, s77, v148
	s_add_i32 s78, 0, 0x1c000
	s_nop 1
	ds_read_b128 v[0:3], v8
	ds_read_b128 v[4:7], v8 offset:1024
	ds_read_b128 v[16:19], v8 offset:2048
	ds_read_b128 v[20:23], v8 offset:3072
	v_add_u32_e32 v8, s78, v148
	ds_read_b128 v[128:131], v8
	ds_read_b128 v[132:135], v8 offset:1024
	ds_read_b128 v[154:157], v8 offset:2048
	ds_read_b128 v[158:161], v8 offset:3072
	s_add_u32 s10, s50, 0x80000
	s_addc_u32 s11, s51, 0
	s_mov_b32 m0, s63
	ds_read_b128 v[8:11], v151 offset:32768
	ds_read_b128 v[12:15], v151 offset:33792
	ds_read_b128 v[24:27], v151 offset:34816
	ds_read_b128 v[28:31], v151 offset:35840
	ds_read_b128 v[32:35], v151 offset:36864
	ds_read_b128 v[36:39], v151 offset:37888
	ds_read_b128 v[40:43], v151 offset:38912
	ds_read_b128 v[44:47], v151 offset:39936
	global_load_lds_dwordx4 v136, s[10:11]
	s_mov_b32 m0, s64
	s_nop 0
	global_load_lds_dwordx4 v140, s[10:11]
	s_waitcnt vmcnt(8)
	s_waitcnt lgkmcnt(0)
	s_setprio 1
	s_barrier
	v_mfma_scale_f32_16x16x128_f8f6f4 v[124:127], v[0:7], v[8:15], v[124:127], v152, v152 op_sel_hi:[0,0,0]
	v_mfma_scale_f32_16x16x128_f8f6f4 v[120:123], v[16:23], v[8:15], v[120:123], v152, v152 op_sel_hi:[0,0,0]
	v_mfma_scale_f32_16x16x128_f8f6f4 v[108:111], v[0:7], v[24:31], v[108:111], v152, v152 op_sel_hi:[0,0,0]
	v_mfma_scale_f32_16x16x128_f8f6f4 v[104:107], v[16:23], v[24:31], v[104:107], v152, v152 op_sel_hi:[0,0,0]
	v_mfma_scale_f32_16x16x128_f8f6f4 v[92:95], v[0:7], v[32:39], v[210:213], v152, v152 op_sel_hi:[0,0,0]
	v_mfma_scale_f32_16x16x128_f8f6f4 v[88:91], v[16:23], v[32:39], v[214:217], v152, v152 op_sel_hi:[0,0,0]
	v_mfma_scale_f32_16x16x128_f8f6f4 v[76:79], v[0:7], v[40:47], v[218:221], v152, v152 op_sel_hi:[0,0,0]
	v_mfma_scale_f32_16x16x128_f8f6f4 v[72:75], v[16:23], v[40:47], v[222:225], v152, v152 op_sel_hi:[0,0,0]
	v_mfma_scale_f32_16x16x128_f8f6f4 v[116:119], v[128:135], v[8:15], v[116:119], v152, v152 op_sel_hi:[0,0,0]
	v_mfma_scale_f32_16x16x128_f8f6f4 v[112:115], v[154:161], v[8:15], v[112:115], v152, v152 op_sel_hi:[0,0,0]
	v_mfma_scale_f32_16x16x128_f8f6f4 v[100:103], v[128:135], v[24:31], v[100:103], v152, v152 op_sel_hi:[0,0,0]
	v_mfma_scale_f32_16x16x128_f8f6f4 v[96:99], v[154:161], v[24:31], v[96:99], v152, v152 op_sel_hi:[0,0,0]
	v_mfma_scale_f32_16x16x128_f8f6f4 v[84:87], v[128:135], v[32:39], v[178:181], v152, v152 op_sel_hi:[0,0,0]
	v_mfma_scale_f32_16x16x128_f8f6f4 v[80:83], v[154:161], v[32:39], v[182:185], v152, v152 op_sel_hi:[0,0,0]
	v_mfma_scale_f32_16x16x128_f8f6f4 v[68:71], v[128:135], v[40:47], v[186:189], v152, v152 op_sel_hi:[0,0,0]
	v_mfma_scale_f32_16x16x128_f8f6f4 v[64:67], v[154:161], v[40:47], v[190:193], v152, v152 op_sel_hi:[0,0,0]
	s_barrier
	s_setprio 0
	s_add_u32 s10, s48, 0x80
	s_addc_u32 s11, s49, 0
	s_add_i32 s50, s77, s56
	s_mov_b32 m0, s50
	ds_read_b128 v[32:35], v151 offset:49152
	ds_read_b128 v[36:39], v151 offset:50176
	ds_read_b128 v[162:165], v151 offset:51200
	ds_read_b128 v[166:169], v151 offset:52224
	ds_read_b128 v[170:173], v151 offset:53248
	ds_read_b128 v[174:177], v151 offset:54272
	ds_read_b128 v[178:181], v151 offset:55296
	ds_read_b128 v[182:185], v151 offset:56320
	global_load_lds_dwordx4 v138, s[10:11]
	s_add_i32 m0, s50, 0x2000
	v_lshl_add_u64 v[8:9], s[10:11], 0, v[142:143]
	s_add_u32 s10, s48, 0x80080
	s_addc_u32 s11, s49, 0
	s_add_i32 s48, s78, s56
	global_load_lds_dwordx4 v[8:9], off
	s_mov_b32 m0, s48
	s_nop 0
	global_load_lds_dwordx4 v138, s[10:11]
	s_add_i32 m0, s48, 0x2000
	s_nop 0
	global_load_lds_dwordx4 v142, s[10:11]
	s_waitcnt vmcnt(4)
	s_waitcnt lgkmcnt(0)
	s_setprio 1
	s_barrier
	v_mfma_scale_f32_16x16x128_f8f6f4 v[60:63], v[0:7], v[32:39], v[60:63], v152, v152 op_sel_hi:[0,0,0]
	v_mfma_scale_f32_16x16x128_f8f6f4 v[56:59], v[16:23], v[32:39], v[56:59], v152, v152 op_sel_hi:[0,0,0]
	v_mfma_scale_f32_16x16x128_f8f6f4 v[44:47], v[0:7], v[162:169], v[194:197], v152, v152 op_sel_hi:[0,0,0]
	v_mfma_scale_f32_16x16x128_f8f6f4 v[40:43], v[16:23], v[162:169], v[198:201], v152, v152 op_sel_hi:[0,0,0]
	v_mfma_scale_f32_16x16x128_f8f6f4 v[28:31], v[0:7], v[170:177], v[202:205], v152, v152 op_sel_hi:[0,0,0]
	v_mfma_scale_f32_16x16x128_f8f6f4 v[24:27], v[16:23], v[170:177], v[206:209], v152, v152 op_sel_hi:[0,0,0]
	v_mfma_scale_f32_16x16x128_f8f6f4 v[12:15], v[0:7], v[178:185], v[226:229], v152, v152 op_sel_hi:[0,0,0]
	v_mfma_scale_f32_16x16x128_f8f6f4 v[8:11], v[16:23], v[178:185], v[230:233], v152, v152 op_sel_hi:[0,0,0]
	v_mfma_scale_f32_16x16x128_f8f6f4 v[52:55], v[128:135], v[32:39], v[52:55], v152, v152 op_sel_hi:[0,0,0]
	v_mfma_scale_f32_16x16x128_f8f6f4 v[48:51], v[154:161], v[32:39], v[48:51], v152, v152 op_sel_hi:[0,0,0]
	v_mfma_scale_f32_16x16x128_f8f6f4 v[36:39], v[128:135], v[162:169], v[234:237], v152, v152 op_sel_hi:[0,0,0]
	v_mfma_scale_f32_16x16x128_f8f6f4 v[32:35], v[154:161], v[162:169], v[238:241], v152, v152 op_sel_hi:[0,0,0]
	v_mfma_scale_f32_16x16x128_f8f6f4 v[20:23], v[128:135], v[170:177], v[242:245], v152, v152 op_sel_hi:[0,0,0]
	v_mfma_scale_f32_16x16x128_f8f6f4 v[16:19], v[154:161], v[170:177], v[246:249], v152, v152 op_sel_hi:[0,0,0]
	v_mfma_scale_f32_16x16x128_f8f6f4 v[4:7], v[128:135], v[178:185], v[250:253], v152, v152 op_sel_hi:[0,0,0]
	v_mfma_scale_f32_16x16x128_f8f6f4 v[0:3], v[154:161], v[178:185], v[144:147], v152, v152 op_sel_hi:[0,0,0]
	s_barrier
	s_setprio 0
	s_add_i32 s76, s76, 2
	s_add_u32 s74, s74, 0x100
	s_addc_u32 s75, s75, 0
	s_cmp_gt_u32 s76, 29
	s_mov_b64 s[10:11], s[26:27]
	s_cbranch_scc0 .LBB0_1200
	s_and_b64 vcc, exec, s[36:37]
	s_cbranch_vccz .LBB0_1203
	s_barrier

; #define PG8_WAIT_V(n) asm volatile("s_waitcnt vmcnt(" #n ")" ::: "memory")
; #define PG8_WAIT_L(n) asm volatile("s_waitcnt lgkmcnt(" #n ")" ::: "memory")
; #define PG8_BAR __builtin_amdgcn_s_barrier()
; #define PG8_SCHED __builtin_amdgcn_sched_barrier(0)
;     ...
;             PG8_LDB(B0, 0, 0); PG8_LDB(B1, 0, 1); PG8_SCHED; PG8_LDA(At, 0, 0); PG8_STAGE(PG8_SA(1, 1), a1 + hstepA, voffA);
;             PG8_WAIT_V(8); PG8_WAIT_L(0); PG8_BAR; PG8_MMA(0, 0, At, B0); PG8_MMA(0, 1, At, B1); PG8_BAR; PG8_SCHED;
;             if constexpr (!HALFU) PG8_LDA(At, 0, 1); PG8_STAGE(PG8_SB(0, 0), b2, voffB); PG8_STAGE(PG8_SB(0, 1), b2 + hstep, voffB); PG8_STAGE(PG8_SA(0, 0), a2, voffA);
;             PG8_WAIT_V(8); PG8_WAIT_L(0); PG8_BAR; if constexpr (!HALFU) { PG8_MMA(1, 0, At, B0); PG8_MMA(1, 1, At, B1); } PG8_BAR; PG8_SCHED;
.LBB0_1370:
	s_add_u32 s98, s10, 0x80
	s_addc_u32 s99, s11, 0
	s_mov_b32 m0, s67
	s_nop 0
	global_load_lds_dwordx4 v136, s[98:99]
	s_mov_b32 m0, s68
	s_nop 0
	global_load_lds_dwordx4 v140, s[98:99]
	ds_read_b128 v[128:131], v163
	ds_read_b128 v[132:135], v163 offset:1024
	ds_read_b128 v[150:153], v163 offset:2048
	ds_read_b128 v[154:157], v163 offset:3072
	ds_read_b128 v[158:161], v164
	ds_read_b128 v[166:169], v164 offset:1024
	ds_read_b128 v[170:173], v164 offset:2048
	ds_read_b128 v[174:177], v164 offset:3072
	s_add_u32 s12, s10, 0x100
	s_addc_u32 s13, s11, 0
	s_cmp_eq_u32 s53, 60
	s_cselect_b32 s50, s7, s12
	s_cselect_b32 s51, s0, s13
	s_cselect_b32 s48, s39, s41
	s_cselect_b32 s49, s9, s52
	s_add_u32 s46, s50, 0x80
	s_addc_u32 s47, s51, 0
	s_add_u32 s10, s10, 0x100080
	s_addc_u32 s11, s11, 0
	s_add_i32 m0, s37, 0xc000
	ds_read_b128 v[178:181], v165
	ds_read_b128 v[182:185], v165 offset:1024
	ds_read_b128 v[186:189], v165 offset:2048
	ds_read_b128 v[190:193], v165 offset:3072
	ds_read_b128 v[194:197], v165 offset:4096
	ds_read_b128 v[198:201], v165 offset:5120
	ds_read_b128 v[202:205], v165 offset:6144
	ds_read_b128 v[206:209], v165 offset:7168
	global_load_lds_dwordx4 v136, s[10:11]
	s_add_i32 m0, s37, 0xe000
	s_nop 0
	global_load_lds_dwordx4 v140, s[10:11]
	s_waitcnt vmcnt(8)
	s_waitcnt lgkmcnt(0)
	s_setprio 1
	s_barrier
	v_mfma_f32_16x16x32_bf16 v[124:127], v[128:131], v[178:181], v[124:127]
	v_mfma_f32_16x16x32_bf16 v[120:123], v[150:153], v[178:181], v[120:123]
	v_mfma_f32_16x16x32_bf16 v[108:111], v[128:131], v[186:189], v[108:111]
	v_mfma_f32_16x16x32_bf16 v[104:107], v[150:153], v[186:189], v[104:107]
	v_mfma_f32_16x16x32_bf16 v[92:95], v[128:131], v[194:197], v[92:95]
	v_mfma_f32_16x16x32_bf16 v[88:91], v[150:153], v[194:197], v[88:91]
	v_mfma_f32_16x16x32_bf16 v[76:79], v[128:131], v[202:205], v[76:79]
	v_mfma_f32_16x16x32_bf16 v[72:75], v[150:153], v[202:205], v[72:75]
	v_mfma_f32_16x16x32_bf16 v[124:127], v[132:135], v[182:185], v[124:127]
	v_mfma_f32_16x16x32_bf16 v[120:123], v[154:157], v[182:185], v[120:123]
	v_mfma_f32_16x16x32_bf16 v[108:111], v[132:135], v[190:193], v[108:111]
	v_mfma_f32_16x16x32_bf16 v[104:107], v[154:157], v[190:193], v[104:107]
	v_mfma_f32_16x16x32_bf16 v[92:95], v[132:135], v[198:201], v[92:95]
	v_mfma_f32_16x16x32_bf16 v[88:91], v[154:157], v[198:201], v[88:91]
	v_mfma_f32_16x16x32_bf16 v[76:79], v[132:135], v[206:209], v[76:79]
	v_mfma_f32_16x16x32_bf16 v[72:75], v[154:157], v[206:209], v[72:75]
	v_mfma_f32_16x16x32_bf16 v[116:119], v[158:161], v[178:181], v[116:119]
	v_mfma_f32_16x16x32_bf16 v[112:115], v[170:173], v[178:181], v[112:115]
	v_mfma_f32_16x16x32_bf16 v[100:103], v[158:161], v[186:189], v[100:103]
	v_mfma_f32_16x16x32_bf16 v[96:99], v[170:173], v[186:189], v[96:99]
	v_mfma_f32_16x16x32_bf16 v[84:87], v[158:161], v[194:197], v[84:87]
	v_mfma_f32_16x16x32_bf16 v[80:83], v[170:173], v[194:197], v[80:83]
	v_mfma_f32_16x16x32_bf16 v[68:71], v[158:161], v[202:205], v[68:71]
	v_mfma_f32_16x16x32_bf16 v[64:67], v[170:173], v[202:205], v[64:67]
	v_mfma_f32_16x16x32_bf16 v[116:119], v[166:169], v[182:185], v[116:119]
	v_mfma_f32_16x16x32_bf16 v[112:115], v[174:177], v[182:185], v[112:115]
	v_mfma_f32_16x16x32_bf16 v[100:103], v[166:169], v[190:193], v[100:103]
	v_mfma_f32_16x16x32_bf16 v[96:99], v[174:177], v[190:193], v[96:99]
	v_mfma_f32_16x16x32_bf16 v[84:87], v[166:169], v[198:201], v[84:87]
	v_mfma_f32_16x16x32_bf16 v[80:83], v[174:177], v[198:201], v[80:83]
	v_mfma_f32_16x16x32_bf16 v[68:71], v[166:169], v[206:209], v[68:71]
	v_mfma_f32_16x16x32_bf16 v[64:67], v[174:177], v[206:209], v[64:67]
	s_barrier
	s_setprio 0
	s_add_i32 s10, s71, s21
	s_mov_b32 m0, s10
	ds_read_b128 v[178:181], v165 offset:16384
	ds_read_b128 v[182:185], v165 offset:17408
	ds_read_b128 v[186:189], v165 offset:18432
	ds_read_b128 v[190:193], v165 offset:19456
	ds_read_b128 v[194:197], v165 offset:20480
	ds_read_b128 v[198:201], v165 offset:21504
	ds_read_b128 v[202:205], v165 offset:22528
	ds_read_b128 v[206:209], v165 offset:23552
	global_load_lds_dwordx4 v138, s[48:49]
	s_add_i32 m0, s10, 0x2000
	s_add_u32 s10, s48, 0x100000
	s_addc_u32 s11, s49, 0
	s_add_i32 s54, s72, s21
	global_load_lds_dwordx4 v142, s[48:49]
	s_mov_b32 m0, s54
	s_nop 0
	global_load_lds_dwordx4 v138, s[10:11]
	s_add_i32 m0, s54, 0x2000
	s_nop 0
	global_load_lds_dwordx4 v142, s[10:11]
	s_waitcnt vmcnt(4)
	s_waitcnt lgkmcnt(0)
	s_setprio 1
	s_barrier
	v_mfma_f32_16x16x32_bf16 v[60:63], v[128:131], v[178:181], v[60:63]
	v_mfma_f32_16x16x32_bf16 v[56:59], v[150:153], v[178:181], v[56:59]
	v_mfma_f32_16x16x32_bf16 v[44:47], v[128:131], v[186:189], v[44:47]
	v_mfma_f32_16x16x32_bf16 v[40:43], v[150:153], v[186:189], v[40:43]
	v_mfma_f32_16x16x32_bf16 v[28:31], v[128:131], v[194:197], v[28:31]
	v_mfma_f32_16x16x32_bf16 v[24:27], v[150:153], v[194:197], v[24:27]
	v_mfma_f32_16x16x32_bf16 v[12:15], v[128:131], v[202:205], v[12:15]
	v_mfma_f32_16x16x32_bf16 v[8:11], v[150:153], v[202:205], v[8:11]
	v_mfma_f32_16x16x32_bf16 v[60:63], v[132:135], v[182:185], v[60:63]
	v_mfma_f32_16x16x32_bf16 v[56:59], v[154:157], v[182:185], v[56:59]
	v_mfma_f32_16x16x32_bf16 v[44:47], v[132:135], v[190:193], v[44:47]
	v_mfma_f32_16x16x32_bf16 v[40:43], v[154:157], v[190:193], v[40:43]
	v_mfma_f32_16x16x32_bf16 v[28:31], v[132:135], v[198:201], v[28:31]
	v_mfma_f32_16x16x32_bf16 v[24:27], v[154:157], v[198:201], v[24:27]
	v_mfma_f32_16x16x32_bf16 v[12:15], v[132:135], v[206:209], v[12:15]
	v_mfma_f32_16x16x32_bf16 v[8:11], v[154:157], v[206:209], v[8:11]
	v_mfma_f32_16x16x32_bf16 v[52:55], v[158:161], v[178:181], v[52:55]
	v_mfma_f32_16x16x32_bf16 v[48:51], v[170:173], v[178:181], v[48:51]
	v_mfma_f32_16x16x32_bf16 v[36:39], v[158:161], v[186:189], v[36:39]
	v_mfma_f32_16x16x32_bf16 v[32:35], v[170:173], v[186:189], v[32:35]
	v_mfma_f32_16x16x32_bf16 v[20:23], v[158:161], v[194:197], v[20:23]
	v_mfma_f32_16x16x32_bf16 v[16:19], v[170:173], v[194:197], v[16:19]
	v_mfma_f32_16x16x32_bf16 v[4:7], v[158:161], v[202:205], v[4:7]
	v_mfma_f32_16x16x32_bf16 v[0:3], v[170:173], v[202:205], v[0:3]
	v_mfma_f32_16x16x32_bf16 v[52:55], v[166:169], v[182:185], v[52:55]
	v_mfma_f32_16x16x32_bf16 v[48:51], v[174:177], v[182:185], v[48:51]
	v_mfma_f32_16x16x32_bf16 v[36:39], v[166:169], v[190:193], v[36:39]
	v_mfma_f32_16x16x32_bf16 v[32:35], v[174:177], v[190:193], v[32:35]
	v_mfma_f32_16x16x32_bf16 v[20:23], v[166:169], v[198:201], v[20:23]
	v_mfma_f32_16x16x32_bf16 v[16:19], v[174:177], v[198:201], v[16:19]
	v_mfma_f32_16x16x32_bf16 v[4:7], v[166:169], v[206:209], v[4:7]
	v_mfma_f32_16x16x32_bf16 v[0:3], v[174:177], v[206:209], v[0:3]
	s_barrier
; #define PG8_WAIT_V(n) asm volatile("s_waitcnt vmcnt(" #n ")" ::: "memory")
; #define PG8_WAIT_L(n) asm volatile("s_waitcnt lgkmcnt(" #n ")" ::: "memory")
; #define PG8_BAR __builtin_amdgcn_s_barrier()
; #define PG8_SCHED __builtin_amdgcn_sched_barrier(0)
;     ...
;         for (int t = 0; t < nt; t += 2) {
;             const bool last = (t == nt - 2);
;             const char* a1 = cA + (size_t)(t + 1) * kstep;
;             const char* a2 = last ? nA : cA + (size_t)(t + 2) * kstep; const char* b2 = last ? nB : cB + (size_t)(t + 2) * kstep;
;             const char* a3 = a2 + kstep; const char* b3 = b2 + kstep;
;             if (last && has_next) S.a_ready(nxt);
;     ...
;             PG8_LDB(B0, 1, 0); PG8_LDB(B1, 1, 1); PG8_SCHED; PG8_LDA(At, 1, 0); PG8_STAGE(PG8_SA(0, 1), a2 + hstepA, voffA);
;             PG8_WAIT_V(8); PG8_WAIT_L(0); PG8_BAR; PG8_MMA(0, 0, At, B0); PG8_MMA(0, 1, At, B1); PG8_BAR; PG8_SCHED;
;             if constexpr (!HALFU) PG8_LDA(At, 1, 1); PG8_STAGE(PG8_SB(1, 0), b3, voffB); PG8_STAGE(PG8_SB(1, 1), b3 + hstep, voffB); PG8_STAGE(PG8_SA(1, 0), a3, voffA);
;             PG8_WAIT_V(8); PG8_WAIT_L(0); PG8_BAR; if constexpr (!HALFU) { PG8_MMA(1, 0, At, B0); PG8_MMA(1, 1, At, B1); } PG8_BAR; PG8_SCHED;
	s_setprio 0
	s_mov_b32 m0, s37
	s_nop 0
	global_load_lds_dwordx4 v136, s[50:51]
	s_mov_b32 m0, s62
	s_nop 0
	global_load_lds_dwordx4 v140, s[50:51]
	s_add_i32 s54, 0, 0x18000
	v_add_u32_e32 v144, s54, v162
	s_add_i32 s55, 0, 0x1c000
	ds_read_b128 v[128:131], v144
	ds_read_b128 v[132:135], v144 offset:1024
	ds_read_b128 v[150:153], v144 offset:2048
	ds_read_b128 v[154:157], v144 offset:3072
	v_add_u32_e32 v144, s55, v162
	ds_read_b128 v[158:161], v144
	ds_read_b128 v[166:169], v144 offset:1024
	ds_read_b128 v[170:173], v144 offset:2048
	ds_read_b128 v[174:177], v144 offset:3072
	s_add_u32 s10, s50, 0x100000
	s_addc_u32 s11, s51, 0
	s_mov_b32 m0, s63
	ds_read_b128 v[178:181], v165 offset:32768
	ds_read_b128 v[182:185], v165 offset:33792
	ds_read_b128 v[186:189], v165 offset:34816
	ds_read_b128 v[190:193], v165 offset:35840
	ds_read_b128 v[194:197], v165 offset:36864
	ds_read_b128 v[198:201], v165 offset:37888
	ds_read_b128 v[202:205], v165 offset:38912
	ds_read_b128 v[206:209], v165 offset:39936
	global_load_lds_dwordx4 v136, s[10:11]
	s_mov_b32 m0, s64
	s_nop 0
	global_load_lds_dwordx4 v140, s[10:11]
	s_waitcnt vmcnt(8)
	s_waitcnt lgkmcnt(0)
	s_setprio 1
	s_barrier
	v_mfma_f32_16x16x32_bf16 v[124:127], v[128:131], v[178:181], v[124:127]
	v_mfma_f32_16x16x32_bf16 v[120:123], v[150:153], v[178:181], v[120:123]
	v_mfma_f32_16x16x32_bf16 v[108:111], v[128:131], v[186:189], v[108:111]
	v_mfma_f32_16x16x32_bf16 v[104:107], v[150:153], v[186:189], v[104:107]
	v_mfma_f32_16x16x32_bf16 v[92:95], v[128:131], v[194:197], v[92:95]
	v_mfma_f32_16x16x32_bf16 v[88:91], v[150:153], v[194:197], v[88:91]
	v_mfma_f32_16x16x32_bf16 v[76:79], v[128:131], v[202:205], v[76:79]
	v_mfma_f32_16x16x32_bf16 v[72:75], v[150:153], v[202:205], v[72:75]
	v_mfma_f32_16x16x32_bf16 v[124:127], v[132:135], v[182:185], v[124:127]
	v_mfma_f32_16x16x32_bf16 v[120:123], v[154:157], v[182:185], v[120:123]
	v_mfma_f32_16x16x32_bf16 v[108:111], v[132:135], v[190:193], v[108:111]
	v_mfma_f32_16x16x32_bf16 v[104:107], v[154:157], v[190:193], v[104:107]
	v_mfma_f32_16x16x32_bf16 v[92:95], v[132:135], v[198:201], v[92:95]
	v_mfma_f32_16x16x32_bf16 v[88:91], v[154:157], v[198:201], v[88:91]
	v_mfma_f32_16x16x32_bf16 v[76:79], v[132:135], v[206:209], v[76:79]
	v_mfma_f32_16x16x32_bf16 v[72:75], v[154:157], v[206:209], v[72:75]
	v_mfma_f32_16x16x32_bf16 v[116:119], v[158:161], v[178:181], v[116:119]
	v_mfma_f32_16x16x32_bf16 v[112:115], v[170:173], v[178:181], v[112:115]
	v_mfma_f32_16x16x32_bf16 v[100:103], v[158:161], v[186:189], v[100:103]
	v_mfma_f32_16x16x32_bf16 v[96:99], v[170:173], v[186:189], v[96:99]
	v_mfma_f32_16x16x32_bf16 v[84:87], v[158:161], v[194:197], v[84:87]
	v_mfma_f32_16x16x32_bf16 v[80:83], v[170:173], v[194:197], v[80:83]
	v_mfma_f32_16x16x32_bf16 v[68:71], v[158:161], v[202:205], v[68:71]
	v_mfma_f32_16x16x32_bf16 v[64:67], v[170:173], v[202:205], v[64:67]
	v_mfma_f32_16x16x32_bf16 v[116:119], v[166:169], v[182:185], v[116:119]
	v_mfma_f32_16x16x32_bf16 v[112:115], v[174:177], v[182:185], v[112:115]
	v_mfma_f32_16x16x32_bf16 v[100:103], v[166:169], v[190:193], v[100:103]
	v_mfma_f32_16x16x32_bf16 v[96:99], v[174:177], v[190:193], v[96:99]
	v_mfma_f32_16x16x32_bf16 v[84:87], v[166:169], v[198:201], v[84:87]
	v_mfma_f32_16x16x32_bf16 v[80:83], v[174:177], v[198:201], v[80:83]
	v_mfma_f32_16x16x32_bf16 v[68:71], v[166:169], v[206:209], v[68:71]
	v_mfma_f32_16x16x32_bf16 v[64:67], v[174:177], v[206:209], v[64:67]
	s_barrier
	s_setprio 0
	s_add_u32 s10, s48, 0x80
	s_addc_u32 s11, s49, 0
	s_add_i32 s50, s54, s21
	s_mov_b32 m0, s50
	ds_read_b128 v[178:181], v165 offset:49152
	ds_read_b128 v[182:185], v165 offset:50176
	ds_read_b128 v[186:189], v165 offset:51200
	ds_read_b128 v[190:193], v165 offset:52224
	ds_read_b128 v[194:197], v165 offset:53248
	ds_read_b128 v[198:201], v165 offset:54272
	ds_read_b128 v[202:205], v165 offset:55296
	ds_read_b128 v[206:209], v165 offset:56320
	global_load_lds_dwordx4 v138, s[10:11]
	s_add_i32 m0, s50, 0x2000
	v_lshl_add_u64 v[210:211], s[10:11], 0, v[142:143]
	s_add_u32 s10, s48, 0x100080
	s_addc_u32 s11, s49, 0
	s_add_i32 s48, s55, s21
	global_load_lds_dwordx4 v[210:211], off
	s_mov_b32 m0, s48
	s_nop 0
	global_load_lds_dwordx4 v138, s[10:11]
	s_add_i32 m0, s48, 0x2000
	s_nop 0
	global_load_lds_dwordx4 v142, s[10:11]
	s_waitcnt vmcnt(4)
	s_waitcnt lgkmcnt(0)
	s_setprio 1
	s_barrier
	v_mfma_f32_16x16x32_bf16 v[60:63], v[128:131], v[178:181], v[60:63]
	v_mfma_f32_16x16x32_bf16 v[56:59], v[150:153], v[178:181], v[56:59]
	v_mfma_f32_16x16x32_bf16 v[44:47], v[128:131], v[186:189], v[44:47]
	v_mfma_f32_16x16x32_bf16 v[40:43], v[150:153], v[186:189], v[40:43]
	v_mfma_f32_16x16x32_bf16 v[28:31], v[128:131], v[194:197], v[28:31]
	v_mfma_f32_16x16x32_bf16 v[24:27], v[150:153], v[194:197], v[24:27]
	v_mfma_f32_16x16x32_bf16 v[12:15], v[128:131], v[202:205], v[12:15]
	v_mfma_f32_16x16x32_bf16 v[8:11], v[150:153], v[202:205], v[8:11]
	v_mfma_f32_16x16x32_bf16 v[60:63], v[132:135], v[182:185], v[60:63]
	v_mfma_f32_16x16x32_bf16 v[56:59], v[154:157], v[182:185], v[56:59]
	v_mfma_f32_16x16x32_bf16 v[44:47], v[132:135], v[190:193], v[44:47]
	v_mfma_f32_16x16x32_bf16 v[40:43], v[154:157], v[190:193], v[40:43]
	v_mfma_f32_16x16x32_bf16 v[28:31], v[132:135], v[198:201], v[28:31]
	v_mfma_f32_16x16x32_bf16 v[24:27], v[154:157], v[198:201], v[24:27]
	v_mfma_f32_16x16x32_bf16 v[12:15], v[132:135], v[206:209], v[12:15]
	v_mfma_f32_16x16x32_bf16 v[8:11], v[154:157], v[206:209], v[8:11]
	v_mfma_f32_16x16x32_bf16 v[52:55], v[158:161], v[178:181], v[52:55]
	v_mfma_f32_16x16x32_bf16 v[48:51], v[170:173], v[178:181], v[48:51]
	v_mfma_f32_16x16x32_bf16 v[36:39], v[158:161], v[186:189], v[36:39]
	v_mfma_f32_16x16x32_bf16 v[32:35], v[170:173], v[186:189], v[32:35]
	v_mfma_f32_16x16x32_bf16 v[20:23], v[158:161], v[194:197], v[20:23]
	v_mfma_f32_16x16x32_bf16 v[16:19], v[170:173], v[194:197], v[16:19]
	v_mfma_f32_16x16x32_bf16 v[4:7], v[158:161], v[202:205], v[4:7]
	v_mfma_f32_16x16x32_bf16 v[0:3], v[170:173], v[202:205], v[0:3]
	v_mfma_f32_16x16x32_bf16 v[52:55], v[166:169], v[182:185], v[52:55]
	v_mfma_f32_16x16x32_bf16 v[48:51], v[174:177], v[182:185], v[48:51]
	v_mfma_f32_16x16x32_bf16 v[36:39], v[166:169], v[190:193], v[36:39]
	v_mfma_f32_16x16x32_bf16 v[32:35], v[174:177], v[190:193], v[32:35]
	v_mfma_f32_16x16x32_bf16 v[20:23], v[166:169], v[198:201], v[20:23]
	v_mfma_f32_16x16x32_bf16 v[16:19], v[174:177], v[198:201], v[16:19]
	v_mfma_f32_16x16x32_bf16 v[4:7], v[166:169], v[206:209], v[4:7]
	v_mfma_f32_16x16x32_bf16 v[0:3], v[174:177], v[206:209], v[0:3]
	s_barrier
	s_setprio 0
	s_add_i32 s53, s53, 2
	s_add_u32 s41, s41, 0x100
	s_addc_u32 s52, s52, 0
	s_cmp_gt_u32 s53, 61
	s_mov_b64 s[10:11], s[12:13]
	s_cbranch_scc0 .LBB0_1370
	s_and_b64 vcc, exec, s[28:29]
	s_cbranch_vccz .LBB0_1373
	s_barrier

; #define PG8_WAIT_V(n) asm volatile("s_waitcnt vmcnt(" #n ")" ::: "memory")
; #define PG8_WAIT_L(n) asm volatile("s_waitcnt lgkmcnt(" #n ")" ::: "memory")
; #define PG8_BAR __builtin_amdgcn_s_barrier()
; #define PG8_SCHED __builtin_amdgcn_sched_barrier(0)
;     ...
;             PG8_LDB(B0, 0, 0); PG8_LDB(B1, 0, 1); PG8_SCHED; PG8_LDA(At, 0, 0); PG8_STAGE(PG8_SA(1, 1), a1 + hstepA, voffA);
;             PG8_WAIT_V(8); PG8_WAIT_L(0); PG8_BAR; PG8_MMA(0, 0, At, B0); PG8_MMA(0, 1, At, B1); PG8_BAR; PG8_SCHED;
;             if constexpr (!HALFU) PG8_LDA(At, 0, 1); PG8_STAGE(PG8_SB(0, 0), b2, voffB); PG8_STAGE(PG8_SB(0, 1), b2 + hstep, voffB); PG8_STAGE(PG8_SA(0, 0), a2, voffA);
;             PG8_WAIT_V(8); PG8_WAIT_L(0); PG8_BAR; if constexpr (!HALFU) { PG8_MMA(1, 0, At, B0); PG8_MMA(1, 1, At, B1); } PG8_BAR; PG8_SCHED;
.LBB0_3426:
	s_sub_u32 s98, s28, 0x80000
	s_subb_u32 s99, s29, 0
	s_mov_b32 m0, s50
	s_nop 0
	global_load_lds_dwordx4 v128, s[98:99]
	s_mov_b32 m0, s51
	s_nop 0
	global_load_lds_dwordx4 v130, s[98:99]
	ds_read_b128 v[142:145], v137
	ds_read_b128 v[146:149], v137 offset:1024
	ds_read_b128 v[150:153], v137 offset:2048
	ds_read_b128 v[154:157], v137 offset:3072
	ds_read_b128 v[158:161], v138
	ds_read_b128 v[162:165], v138 offset:1024
	ds_read_b128 v[166:169], v138 offset:2048
	ds_read_b128 v[170:173], v138 offset:3072
	s_cmp_eq_u32 s62, 28
	s_cselect_b32 s38, s55, s57
	s_cselect_b32 s39, s23, s59
	s_cselect_b32 s36, s56, s60
	s_cselect_b32 s37, s21, s61
	s_add_u32 s30, s38, 0x80
	s_addc_u32 s31, s39, 0
	s_add_i32 m0, s43, 0xc000
	ds_read_b128 v[174:177], v139
	ds_read_b128 v[178:181], v139 offset:1024
	ds_read_b128 v[182:185], v139 offset:2048
	ds_read_b128 v[186:189], v139 offset:3072
	ds_read_b128 v[190:193], v139 offset:4096
	ds_read_b128 v[194:197], v139 offset:5120
	ds_read_b128 v[198:201], v139 offset:6144
	ds_read_b128 v[202:205], v139 offset:7168
	global_load_lds_dwordx4 v128, s[28:29]
	s_add_i32 m0, s43, 0xe000
	s_nop 0
	global_load_lds_dwordx4 v130, s[28:29]
	s_waitcnt vmcnt(8)
	s_waitcnt lgkmcnt(0)
	s_setprio 1
	s_barrier
	v_mfma_scale_f32_16x16x128_f8f6f4 v[124:127], v[142:149], v[174:181], v[124:127], v140, v140 op_sel_hi:[0,0,0]
	v_mfma_scale_f32_16x16x128_f8f6f4 v[120:123], v[150:157], v[174:181], v[120:123], v140, v140 op_sel_hi:[0,0,0]
	v_mfma_scale_f32_16x16x128_f8f6f4 v[112:115], v[142:149], v[182:189], v[112:115], v140, v140 op_sel_hi:[0,0,0]
	v_mfma_scale_f32_16x16x128_f8f6f4 v[104:107], v[150:157], v[182:189], v[104:107], v140, v140 op_sel_hi:[0,0,0]
	v_mfma_scale_f32_16x16x128_f8f6f4 v[96:99], v[142:149], v[190:197], v[96:99], v140, v140 op_sel_hi:[0,0,0]
	v_mfma_scale_f32_16x16x128_f8f6f4 v[206:209], v[150:157], v[190:197], v[88:91], v140, v140 op_sel_hi:[0,0,0]
	v_mfma_scale_f32_16x16x128_f8f6f4 v[210:213], v[142:149], v[198:205], v[80:83], v140, v140 op_sel_hi:[0,0,0]
	v_mfma_scale_f32_16x16x128_f8f6f4 v[214:217], v[150:157], v[198:205], v[72:75], v140, v140 op_sel_hi:[0,0,0]
	v_mfma_scale_f32_16x16x128_f8f6f4 v[116:119], v[158:165], v[174:181], v[116:119], v140, v140 op_sel_hi:[0,0,0]
	v_mfma_scale_f32_16x16x128_f8f6f4 v[108:111], v[166:173], v[174:181], v[108:111], v140, v140 op_sel_hi:[0,0,0]
	v_mfma_scale_f32_16x16x128_f8f6f4 v[100:103], v[158:165], v[182:189], v[100:103], v140, v140 op_sel_hi:[0,0,0]
	v_mfma_scale_f32_16x16x128_f8f6f4 v[174:177], v[166:173], v[182:189], v[92:95], v140, v140 op_sel_hi:[0,0,0]
	v_mfma_scale_f32_16x16x128_f8f6f4 v[178:181], v[158:165], v[190:197], v[84:87], v140, v140 op_sel_hi:[0,0,0]
	v_mfma_scale_f32_16x16x128_f8f6f4 v[182:185], v[166:173], v[190:197], v[76:79], v140, v140 op_sel_hi:[0,0,0]
	v_mfma_scale_f32_16x16x128_f8f6f4 v[186:189], v[158:165], v[198:205], v[68:71], v140, v140 op_sel_hi:[0,0,0]
	v_mfma_scale_f32_16x16x128_f8f6f4 v[190:193], v[166:173], v[198:205], v[64:67], v140, v140 op_sel_hi:[0,0,0]
	s_barrier
	s_setprio 0
	s_add_i32 s63, s53, s41
	s_mov_b32 m0, s63
	s_nop 1
	ds_read_b128 v[64:67], v139 offset:16384
	ds_read_b128 v[68:71], v139 offset:17408
	ds_read_b128 v[72:75], v139 offset:18432
	ds_read_b128 v[76:79], v139 offset:19456
	ds_read_b128 v[80:83], v139 offset:20480
	ds_read_b128 v[84:87], v139 offset:21504
	ds_read_b128 v[88:91], v139 offset:22528
	ds_read_b128 v[92:95], v139 offset:23552
	global_load_lds_dwordx4 v128, s[36:37]
	s_add_i32 m0, s63, 0x2000
	s_add_u32 s64, s36, 0x80000
	s_addc_u32 s65, s37, 0
	s_add_i32 s63, s54, s41
	global_load_lds_dwordx4 v130, s[36:37]
	s_mov_b32 m0, s63
	s_nop 0
	global_load_lds_dwordx4 v128, s[64:65]
	s_add_i32 m0, s63, 0x2000
	s_nop 0
	global_load_lds_dwordx4 v130, s[64:65]
	s_waitcnt vmcnt(4)
	s_waitcnt lgkmcnt(0)
	s_setprio 1
	s_barrier
	v_mfma_scale_f32_16x16x128_f8f6f4 v[60:63], v[142:149], v[64:71], v[60:63], v140, v140 op_sel_hi:[0,0,0]
	v_mfma_scale_f32_16x16x128_f8f6f4 v[56:59], v[150:157], v[64:71], v[56:59], v140, v140 op_sel_hi:[0,0,0]
	v_mfma_scale_f32_16x16x128_f8f6f4 v[48:51], v[142:149], v[72:79], v[48:51], v140, v140 op_sel_hi:[0,0,0]
	v_mfma_scale_f32_16x16x128_f8f6f4 v[194:197], v[150:157], v[72:79], v[40:43], v140, v140 op_sel_hi:[0,0,0]
	v_mfma_scale_f32_16x16x128_f8f6f4 v[198:201], v[142:149], v[80:87], v[32:35], v140, v140 op_sel_hi:[0,0,0]
	v_mfma_scale_f32_16x16x128_f8f6f4 v[202:205], v[150:157], v[80:87], v[24:27], v140, v140 op_sel_hi:[0,0,0]
	v_mfma_scale_f32_16x16x128_f8f6f4 v[218:221], v[142:149], v[88:95], v[16:19], v140, v140 op_sel_hi:[0,0,0]
	v_mfma_scale_f32_16x16x128_f8f6f4 v[222:225], v[150:157], v[88:95], v[8:11], v140, v140 op_sel_hi:[0,0,0]
	v_mfma_scale_f32_16x16x128_f8f6f4 v[52:55], v[158:165], v[64:71], v[52:55], v140, v140 op_sel_hi:[0,0,0]
	v_mfma_scale_f32_16x16x128_f8f6f4 v[226:229], v[166:173], v[64:71], v[44:47], v140, v140 op_sel_hi:[0,0,0]
	v_mfma_scale_f32_16x16x128_f8f6f4 v[230:233], v[158:165], v[72:79], v[36:39], v140, v140 op_sel_hi:[0,0,0]
	v_mfma_scale_f32_16x16x128_f8f6f4 v[234:237], v[166:173], v[72:79], v[28:31], v140, v140 op_sel_hi:[0,0,0]
	v_mfma_scale_f32_16x16x128_f8f6f4 v[238:241], v[158:165], v[80:87], v[20:23], v140, v140 op_sel_hi:[0,0,0]
	v_mfma_scale_f32_16x16x128_f8f6f4 v[242:245], v[166:173], v[80:87], v[12:15], v140, v140 op_sel_hi:[0,0,0]
	v_mfma_scale_f32_16x16x128_f8f6f4 v[246:249], v[158:165], v[88:95], v[4:7], v140, v140 op_sel_hi:[0,0,0]
	v_mfma_scale_f32_16x16x128_f8f6f4 v[250:253], v[166:173], v[88:95], v[0:3], v140, v140 op_sel_hi:[0,0,0]
	s_barrier
; #define PG8_WAIT_V(n) asm volatile("s_waitcnt vmcnt(" #n ")" ::: "memory")
; #define PG8_WAIT_L(n) asm volatile("s_waitcnt lgkmcnt(" #n ")" ::: "memory")
; #define PG8_BAR __builtin_amdgcn_s_barrier()
; #define PG8_SCHED __builtin_amdgcn_sched_barrier(0)
;     ...
;         for (int t = 0; t < nt; t += 2) {
;             const bool last = (t == nt - 2);
;             const char* a1 = cA + (size_t)(t + 1) * kstep;
;             const char* a2 = last ? nA : cA + (size_t)(t + 2) * kstep; const char* b2 = last ? nB : cB + (size_t)(t + 2) * kstep;
;             const char* a3 = a2 + kstep; const char* b3 = b2 + kstep;
;             if (last && has_next) S.a_ready(nxt);
;     ...
;             PG8_LDB(B0, 1, 0); PG8_LDB(B1, 1, 1); PG8_SCHED; PG8_LDA(At, 1, 0); PG8_STAGE(PG8_SA(0, 1), a2 + hstepA, voffA);
;             PG8_WAIT_V(8); PG8_WAIT_L(0); PG8_BAR; PG8_MMA(0, 0, At, B0); PG8_MMA(0, 1, At, B1); PG8_BAR; PG8_SCHED;
;             if constexpr (!HALFU) PG8_LDA(At, 1, 1); PG8_STAGE(PG8_SB(1, 0), b3, voffB); PG8_STAGE(PG8_SB(1, 1), b3 + hstep, voffB); PG8_STAGE(PG8_SA(1, 0), a3, voffA);
;             PG8_WAIT_V(8); PG8_WAIT_L(0); PG8_BAR; if constexpr (!HALFU) { PG8_MMA(1, 0, At, B0); PG8_MMA(1, 1, At, B1); } PG8_BAR; PG8_SCHED;
	s_setprio 0
	s_mov_b32 m0, s43
	s_nop 0
	global_load_lds_dwordx4 v128, s[38:39]
	s_mov_b32 m0, s44
	s_nop 0
	global_load_lds_dwordx4 v130, s[38:39]
	s_add_i32 s63, 0, 0x18000
	s_add_i32 s64, 0, 0x1c000
	s_nop 0
	v_add_u32_e32 v12, s63, v136
	v_add_u32_e32 v16, s64, v136
	ds_read_b128 v[0:3], v12
	ds_read_b128 v[4:7], v12 offset:1024
	ds_read_b128 v[8:11], v12 offset:2048
	ds_read_b128 v[12:15], v12 offset:3072
	ds_read_b128 v[142:145], v16
	ds_read_b128 v[146:149], v16 offset:1024
	ds_read_b128 v[150:153], v16 offset:2048
	ds_read_b128 v[154:157], v16 offset:3072
	s_add_u32 s38, s38, 0x80000
	s_addc_u32 s39, s39, 0
	s_mov_b32 m0, s45
	ds_read_b128 v[16:19], v139 offset:32768
	ds_read_b128 v[20:23], v139 offset:33792
	ds_read_b128 v[24:27], v139 offset:34816
	ds_read_b128 v[28:31], v139 offset:35840
	ds_read_b128 v[32:35], v139 offset:36864
	ds_read_b128 v[36:39], v139 offset:37888
	ds_read_b128 v[40:43], v139 offset:38912
	ds_read_b128 v[44:47], v139 offset:39936
	global_load_lds_dwordx4 v128, s[38:39]
	s_mov_b32 m0, s46
	s_nop 0
	global_load_lds_dwordx4 v130, s[38:39]
	s_waitcnt vmcnt(8)
	s_waitcnt lgkmcnt(0)
	s_setprio 1
	s_barrier
	v_mfma_scale_f32_16x16x128_f8f6f4 v[124:127], v[0:7], v[16:23], v[124:127], v140, v140 op_sel_hi:[0,0,0]
	v_mfma_scale_f32_16x16x128_f8f6f4 v[120:123], v[8:15], v[16:23], v[120:123], v140, v140 op_sel_hi:[0,0,0]
	v_mfma_scale_f32_16x16x128_f8f6f4 v[112:115], v[0:7], v[24:31], v[112:115], v140, v140 op_sel_hi:[0,0,0]
	v_mfma_scale_f32_16x16x128_f8f6f4 v[104:107], v[8:15], v[24:31], v[104:107], v140, v140 op_sel_hi:[0,0,0]
	v_mfma_scale_f32_16x16x128_f8f6f4 v[96:99], v[0:7], v[32:39], v[96:99], v140, v140 op_sel_hi:[0,0,0]
	v_mfma_scale_f32_16x16x128_f8f6f4 v[88:91], v[8:15], v[32:39], v[206:209], v140, v140 op_sel_hi:[0,0,0]
	v_mfma_scale_f32_16x16x128_f8f6f4 v[80:83], v[0:7], v[40:47], v[210:213], v140, v140 op_sel_hi:[0,0,0]
	v_mfma_scale_f32_16x16x128_f8f6f4 v[72:75], v[8:15], v[40:47], v[214:217], v140, v140 op_sel_hi:[0,0,0]
	v_mfma_scale_f32_16x16x128_f8f6f4 v[116:119], v[142:149], v[16:23], v[116:119], v140, v140 op_sel_hi:[0,0,0]
	v_mfma_scale_f32_16x16x128_f8f6f4 v[108:111], v[150:157], v[16:23], v[108:111], v140, v140 op_sel_hi:[0,0,0]
	v_mfma_scale_f32_16x16x128_f8f6f4 v[100:103], v[142:149], v[24:31], v[100:103], v140, v140 op_sel_hi:[0,0,0]
	v_mfma_scale_f32_16x16x128_f8f6f4 v[92:95], v[150:157], v[24:31], v[174:177], v140, v140 op_sel_hi:[0,0,0]
	v_mfma_scale_f32_16x16x128_f8f6f4 v[84:87], v[142:149], v[32:39], v[178:181], v140, v140 op_sel_hi:[0,0,0]
	v_mfma_scale_f32_16x16x128_f8f6f4 v[76:79], v[150:157], v[32:39], v[182:185], v140, v140 op_sel_hi:[0,0,0]
	v_mfma_scale_f32_16x16x128_f8f6f4 v[68:71], v[142:149], v[40:47], v[186:189], v140, v140 op_sel_hi:[0,0,0]
	v_mfma_scale_f32_16x16x128_f8f6f4 v[64:67], v[150:157], v[40:47], v[190:193], v140, v140 op_sel_hi:[0,0,0]
	s_barrier
	s_setprio 0
	s_add_u32 s38, s36, 0x80
	s_addc_u32 s39, s37, 0
	s_add_i32 s63, s63, s41
	s_mov_b32 m0, s63
	ds_read_b128 v[158:161], v139 offset:49152
	ds_read_b128 v[162:165], v139 offset:50176
	ds_read_b128 v[166:169], v139 offset:51200
	ds_read_b128 v[170:173], v139 offset:52224
	ds_read_b128 v[174:177], v139 offset:53248
	ds_read_b128 v[178:181], v139 offset:54272
	ds_read_b128 v[182:185], v139 offset:55296
	ds_read_b128 v[186:189], v139 offset:56320
	global_load_lds_dwordx4 v128, s[38:39]
	s_add_i32 m0, s63, 0x2000
	s_add_u32 s36, s36, 0x80080
	v_lshl_add_u64 v[16:17], s[38:39], 0, v[130:131]
	s_addc_u32 s37, s37, 0
	s_add_i32 s38, s64, s41
	global_load_lds_dwordx4 v[16:17], off
	s_mov_b32 m0, s38
	s_nop 0
	global_load_lds_dwordx4 v128, s[36:37]
	s_add_i32 m0, s38, 0x2000
	s_nop 0
	global_load_lds_dwordx4 v130, s[36:37]
	s_waitcnt vmcnt(4)
	s_waitcnt lgkmcnt(0)
	s_setprio 1
	s_barrier
	v_mfma_scale_f32_16x16x128_f8f6f4 v[60:63], v[0:7], v[158:165], v[60:63], v140, v140 op_sel_hi:[0,0,0]
	v_mfma_scale_f32_16x16x128_f8f6f4 v[56:59], v[8:15], v[158:165], v[56:59], v140, v140 op_sel_hi:[0,0,0]
	v_mfma_scale_f32_16x16x128_f8f6f4 v[48:51], v[0:7], v[166:173], v[48:51], v140, v140 op_sel_hi:[0,0,0]
	v_mfma_scale_f32_16x16x128_f8f6f4 v[40:43], v[8:15], v[166:173], v[194:197], v140, v140 op_sel_hi:[0,0,0]
	v_mfma_scale_f32_16x16x128_f8f6f4 v[32:35], v[0:7], v[174:181], v[198:201], v140, v140 op_sel_hi:[0,0,0]
	v_mfma_scale_f32_16x16x128_f8f6f4 v[24:27], v[8:15], v[174:181], v[202:205], v140, v140 op_sel_hi:[0,0,0]
	v_mfma_scale_f32_16x16x128_f8f6f4 v[16:19], v[0:7], v[182:189], v[218:221], v140, v140 op_sel_hi:[0,0,0]
	v_mfma_scale_f32_16x16x128_f8f6f4 v[8:11], v[8:15], v[182:189], v[222:225], v140, v140 op_sel_hi:[0,0,0]
	v_mfma_scale_f32_16x16x128_f8f6f4 v[52:55], v[142:149], v[158:165], v[52:55], v140, v140 op_sel_hi:[0,0,0]
	v_mfma_scale_f32_16x16x128_f8f6f4 v[44:47], v[150:157], v[158:165], v[226:229], v140, v140 op_sel_hi:[0,0,0]
	v_mfma_scale_f32_16x16x128_f8f6f4 v[36:39], v[142:149], v[166:173], v[230:233], v140, v140 op_sel_hi:[0,0,0]
	v_mfma_scale_f32_16x16x128_f8f6f4 v[28:31], v[150:157], v[166:173], v[234:237], v140, v140 op_sel_hi:[0,0,0]
	v_mfma_scale_f32_16x16x128_f8f6f4 v[20:23], v[142:149], v[174:181], v[238:241], v140, v140 op_sel_hi:[0,0,0]
	v_mfma_scale_f32_16x16x128_f8f6f4 v[12:15], v[150:157], v[174:181], v[242:245], v140, v140 op_sel_hi:[0,0,0]
	v_mfma_scale_f32_16x16x128_f8f6f4 v[4:7], v[142:149], v[182:189], v[246:249], v140, v140 op_sel_hi:[0,0,0]
	v_mfma_scale_f32_16x16x128_f8f6f4 v[0:3], v[150:157], v[182:189], v[250:253], v140, v140 op_sel_hi:[0,0,0]
	s_barrier
	s_setprio 0
	s_add_i32 s62, s62, 2
	s_add_u32 s57, s57, 0x100
	s_addc_u32 s59, s59, 0
	s_add_u32 s60, s60, 0x100
	s_addc_u32 s61, s61, 0
	s_add_u32 s28, s28, 0x100
	s_addc_u32 s29, s29, 0
	s_cmp_gt_u32 s62, 29
	s_cbranch_scc0 .LBB0_3426
	s_and_b64 vcc, exec, s[6:7]
	s_cbranch_vccz .LBB0_3429
	s_barrier

; #define PG8_WAIT_V(n) asm volatile("s_waitcnt vmcnt(" #n ")" ::: "memory")
; #define PG8_WAIT_L(n) asm volatile("s_waitcnt lgkmcnt(" #n ")" ::: "memory")
; #define PG8_BAR __builtin_amdgcn_s_barrier()
; #define PG8_SCHED __builtin_amdgcn_sched_barrier(0)
;     ...
;             PG8_LDB(B0, 0, 0); PG8_LDB(B1, 0, 1); PG8_SCHED; PG8_LDA(At, 0, 0); PG8_STAGE(PG8_SA(1, 1), a1 + hstepA, voffA);
;             PG8_WAIT_V(8); PG8_WAIT_L(0); PG8_BAR; PG8_MMA(0, 0, At, B0); PG8_MMA(0, 1, At, B1); PG8_BAR; PG8_SCHED;
;             if constexpr (!HALFU) PG8_LDA(At, 0, 1); PG8_STAGE(PG8_SB(0, 0), b2, voffB); PG8_STAGE(PG8_SB(0, 1), b2 + hstep, voffB); PG8_STAGE(PG8_SA(0, 0), a2, voffA);
;             PG8_WAIT_V(8); PG8_WAIT_L(0); PG8_BAR; if constexpr (!HALFU) { PG8_MMA(1, 0, At, B0); PG8_MMA(1, 1, At, B1); } PG8_BAR; PG8_SCHED;
.LBB0_3554:
	s_add_u32 s98, s24, 0x80
	s_addc_u32 s99, s25, 0
	s_mov_b32 m0, s49
	s_nop 0
	global_load_lds_dwordx4 v134, s[98:99]
	s_mov_b32 m0, s50
	s_nop 0
	global_load_lds_dwordx4 v132, s[98:99]
	ds_read_b128 v[144:147], v141
	ds_read_b128 v[148:151], v141 offset:1024
	ds_read_b128 v[152:155], v141 offset:2048
	ds_read_b128 v[156:159], v141 offset:3072
	ds_read_b128 v[160:163], v142
	ds_read_b128 v[164:167], v142 offset:1024
	ds_read_b128 v[168:171], v142 offset:2048
	ds_read_b128 v[172:175], v142 offset:3072
	s_add_u32 s26, s24, 0x100
	s_addc_u32 s27, s25, 0
	s_cmp_eq_u32 s59, 60
	s_cselect_b32 s36, s54, s26
	s_cselect_b32 s37, s15, s27
	s_cselect_b32 s30, s55, s56
	s_cselect_b32 s31, s13, s57
	s_add_u32 s28, s36, 0x80
	s_addc_u32 s29, s37, 0
	s_add_u32 s24, s24, 0x100080
	s_addc_u32 s25, s25, 0
	s_add_i32 m0, s23, 0xc000
	ds_read_b128 v[176:179], v143
	ds_read_b128 v[180:183], v143 offset:1024
	ds_read_b128 v[184:187], v143 offset:2048
	ds_read_b128 v[188:191], v143 offset:3072
	ds_read_b128 v[192:195], v143 offset:4096
	ds_read_b128 v[196:199], v143 offset:5120
	ds_read_b128 v[200:203], v143 offset:6144
	ds_read_b128 v[204:207], v143 offset:7168
	global_load_lds_dwordx4 v134, s[24:25]
	s_add_i32 m0, s23, 0xe000
	s_nop 0
	global_load_lds_dwordx4 v132, s[24:25]
	s_waitcnt vmcnt(8)
	s_waitcnt lgkmcnt(0)
	s_setprio 1
	s_barrier
	v_mfma_f32_16x16x32_bf16 v[124:127], v[144:147], v[176:179], v[124:127]
	v_mfma_f32_16x16x32_bf16 v[120:123], v[152:155], v[176:179], v[120:123]
	v_mfma_f32_16x16x32_bf16 v[108:111], v[144:147], v[184:187], v[108:111]
	v_mfma_f32_16x16x32_bf16 v[104:107], v[152:155], v[184:187], v[104:107]
	v_mfma_f32_16x16x32_bf16 v[92:95], v[144:147], v[192:195], v[92:95]
	v_mfma_f32_16x16x32_bf16 v[88:91], v[152:155], v[192:195], v[88:91]
	v_mfma_f32_16x16x32_bf16 v[76:79], v[144:147], v[200:203], v[76:79]
	v_mfma_f32_16x16x32_bf16 v[72:75], v[152:155], v[200:203], v[72:75]
	v_mfma_f32_16x16x32_bf16 v[124:127], v[148:151], v[180:183], v[124:127]
	v_mfma_f32_16x16x32_bf16 v[120:123], v[156:159], v[180:183], v[120:123]
	v_mfma_f32_16x16x32_bf16 v[108:111], v[148:151], v[188:191], v[108:111]
	v_mfma_f32_16x16x32_bf16 v[104:107], v[156:159], v[188:191], v[104:107]
	v_mfma_f32_16x16x32_bf16 v[92:95], v[148:151], v[196:199], v[92:95]
	v_mfma_f32_16x16x32_bf16 v[88:91], v[156:159], v[196:199], v[88:91]
	v_mfma_f32_16x16x32_bf16 v[76:79], v[148:151], v[204:207], v[76:79]
	v_mfma_f32_16x16x32_bf16 v[72:75], v[156:159], v[204:207], v[72:75]
	v_mfma_f32_16x16x32_bf16 v[116:119], v[160:163], v[176:179], v[116:119]
	v_mfma_f32_16x16x32_bf16 v[112:115], v[168:171], v[176:179], v[112:115]
	v_mfma_f32_16x16x32_bf16 v[100:103], v[160:163], v[184:187], v[100:103]
	v_mfma_f32_16x16x32_bf16 v[96:99], v[168:171], v[184:187], v[96:99]
	v_mfma_f32_16x16x32_bf16 v[84:87], v[160:163], v[192:195], v[84:87]
	v_mfma_f32_16x16x32_bf16 v[80:83], v[168:171], v[192:195], v[80:83]
	v_mfma_f32_16x16x32_bf16 v[68:71], v[160:163], v[200:203], v[68:71]
	v_mfma_f32_16x16x32_bf16 v[64:67], v[168:171], v[200:203], v[64:67]
	v_mfma_f32_16x16x32_bf16 v[116:119], v[164:167], v[180:183], v[116:119]
	v_mfma_f32_16x16x32_bf16 v[112:115], v[172:175], v[180:183], v[112:115]
	v_mfma_f32_16x16x32_bf16 v[100:103], v[164:167], v[188:191], v[100:103]
	v_mfma_f32_16x16x32_bf16 v[96:99], v[172:175], v[188:191], v[96:99]
	v_mfma_f32_16x16x32_bf16 v[84:87], v[164:167], v[196:199], v[84:87]
	v_mfma_f32_16x16x32_bf16 v[80:83], v[172:175], v[196:199], v[80:83]
	v_mfma_f32_16x16x32_bf16 v[68:71], v[164:167], v[204:207], v[68:71]
	v_mfma_f32_16x16x32_bf16 v[64:67], v[172:175], v[204:207], v[64:67]
	s_barrier
	s_setprio 0
	s_add_i32 s24, s6, s40
	s_mov_b32 m0, s24
	ds_read_b128 v[176:179], v143 offset:16384
	ds_read_b128 v[180:183], v143 offset:17408
	ds_read_b128 v[184:187], v143 offset:18432
	ds_read_b128 v[188:191], v143 offset:19456
	ds_read_b128 v[192:195], v143 offset:20480
	ds_read_b128 v[196:199], v143 offset:21504
	ds_read_b128 v[200:203], v143 offset:22528
	ds_read_b128 v[204:207], v143 offset:23552
	global_load_lds_dwordx4 v128, s[30:31]
	s_add_i32 m0, s24, 0x2000
	s_add_u32 s24, s30, 0x100000
	s_addc_u32 s25, s31, 0
	s_add_i32 s60, s51, s40
	global_load_lds_dwordx4 v130, s[30:31]
	s_mov_b32 m0, s60
	s_nop 0
	global_load_lds_dwordx4 v128, s[24:25]
	s_add_i32 m0, s60, 0x2000
	s_nop 0
	global_load_lds_dwordx4 v130, s[24:25]
	s_waitcnt vmcnt(4)
	s_waitcnt lgkmcnt(0)
	s_setprio 1
	s_barrier
	v_mfma_f32_16x16x32_bf16 v[60:63], v[144:147], v[176:179], v[60:63]
	v_mfma_f32_16x16x32_bf16 v[56:59], v[152:155], v[176:179], v[56:59]
	v_mfma_f32_16x16x32_bf16 v[44:47], v[144:147], v[184:187], v[44:47]
	v_mfma_f32_16x16x32_bf16 v[40:43], v[152:155], v[184:187], v[40:43]
	v_mfma_f32_16x16x32_bf16 v[28:31], v[144:147], v[192:195], v[28:31]
	v_mfma_f32_16x16x32_bf16 v[24:27], v[152:155], v[192:195], v[24:27]
	v_mfma_f32_16x16x32_bf16 v[12:15], v[144:147], v[200:203], v[12:15]
	v_mfma_f32_16x16x32_bf16 v[8:11], v[152:155], v[200:203], v[8:11]
	v_mfma_f32_16x16x32_bf16 v[60:63], v[148:151], v[180:183], v[60:63]
	v_mfma_f32_16x16x32_bf16 v[56:59], v[156:159], v[180:183], v[56:59]
	v_mfma_f32_16x16x32_bf16 v[44:47], v[148:151], v[188:191], v[44:47]
	v_mfma_f32_16x16x32_bf16 v[40:43], v[156:159], v[188:191], v[40:43]
	v_mfma_f32_16x16x32_bf16 v[28:31], v[148:151], v[196:199], v[28:31]
	v_mfma_f32_16x16x32_bf16 v[24:27], v[156:159], v[196:199], v[24:27]
	v_mfma_f32_16x16x32_bf16 v[12:15], v[148:151], v[204:207], v[12:15]
	v_mfma_f32_16x16x32_bf16 v[8:11], v[156:159], v[204:207], v[8:11]
	v_mfma_f32_16x16x32_bf16 v[52:55], v[160:163], v[176:179], v[52:55]
	v_mfma_f32_16x16x32_bf16 v[48:51], v[168:171], v[176:179], v[48:51]
	v_mfma_f32_16x16x32_bf16 v[36:39], v[160:163], v[184:187], v[36:39]
	v_mfma_f32_16x16x32_bf16 v[32:35], v[168:171], v[184:187], v[32:35]
	v_mfma_f32_16x16x32_bf16 v[20:23], v[160:163], v[192:195], v[20:23]
	v_mfma_f32_16x16x32_bf16 v[16:19], v[168:171], v[192:195], v[16:19]
	v_mfma_f32_16x16x32_bf16 v[4:7], v[160:163], v[200:203], v[4:7]
	v_mfma_f32_16x16x32_bf16 v[0:3], v[168:171], v[200:203], v[0:3]
	v_mfma_f32_16x16x32_bf16 v[52:55], v[164:167], v[180:183], v[52:55]
	v_mfma_f32_16x16x32_bf16 v[48:51], v[172:175], v[180:183], v[48:51]
	v_mfma_f32_16x16x32_bf16 v[36:39], v[164:167], v[188:191], v[36:39]
	v_mfma_f32_16x16x32_bf16 v[32:35], v[172:175], v[188:191], v[32:35]
	v_mfma_f32_16x16x32_bf16 v[20:23], v[164:167], v[196:199], v[20:23]
	v_mfma_f32_16x16x32_bf16 v[16:19], v[172:175], v[196:199], v[16:19]
	v_mfma_f32_16x16x32_bf16 v[4:7], v[164:167], v[204:207], v[4:7]
	v_mfma_f32_16x16x32_bf16 v[0:3], v[172:175], v[204:207], v[0:3]
	s_barrier
; #define PG8_WAIT_V(n) asm volatile("s_waitcnt vmcnt(" #n ")" ::: "memory")
; #define PG8_WAIT_L(n) asm volatile("s_waitcnt lgkmcnt(" #n ")" ::: "memory")
; #define PG8_BAR __builtin_amdgcn_s_barrier()
; #define PG8_SCHED __builtin_amdgcn_sched_barrier(0)
;     ...
;             PG8_LDB(B0, 1, 0); PG8_LDB(B1, 1, 1); PG8_SCHED; PG8_LDA(At, 1, 0); PG8_STAGE(PG8_SA(0, 1), a2 + hstepA, voffA);
;             PG8_WAIT_V(8); PG8_WAIT_L(0); PG8_BAR; PG8_MMA(0, 0, At, B0); PG8_MMA(0, 1, At, B1); PG8_BAR; PG8_SCHED;
;             if constexpr (!HALFU) PG8_LDA(At, 1, 1); PG8_STAGE(PG8_SB(1, 0), b3, voffB); PG8_STAGE(PG8_SB(1, 1), b3 + hstep, voffB); PG8_STAGE(PG8_SA(1, 0), a3, voffA);
;             PG8_WAIT_V(8); PG8_WAIT_L(0); PG8_BAR; if constexpr (!HALFU) { PG8_MMA(1, 0, At, B0); PG8_MMA(1, 1, At, B1); } PG8_BAR; PG8_SCHED;
	s_setprio 0
	s_mov_b32 m0, s23
	s_nop 0
	global_load_lds_dwordx4 v134, s[36:37]
	s_mov_b32 m0, s43
	s_nop 0
	global_load_lds_dwordx4 v132, s[36:37]
	s_add_i32 s60, 0, 0x18000
	v_add_u32_e32 v138, s60, v140
	s_add_i32 s61, 0, 0x1c000
	ds_read_b128 v[144:147], v138
	ds_read_b128 v[148:151], v138 offset:1024
	ds_read_b128 v[152:155], v138 offset:2048
	ds_read_b128 v[156:159], v138 offset:3072
	v_add_u32_e32 v138, s61, v140
	ds_read_b128 v[160:163], v138
	ds_read_b128 v[164:167], v138 offset:1024
	ds_read_b128 v[168:171], v138 offset:2048
	ds_read_b128 v[172:175], v138 offset:3072
	s_add_u32 s24, s36, 0x100000
	s_addc_u32 s25, s37, 0
	s_mov_b32 m0, s44
	ds_read_b128 v[176:179], v143 offset:32768
	ds_read_b128 v[180:183], v143 offset:33792
	ds_read_b128 v[184:187], v143 offset:34816
	ds_read_b128 v[188:191], v143 offset:35840
	ds_read_b128 v[192:195], v143 offset:36864
	ds_read_b128 v[196:199], v143 offset:37888
	ds_read_b128 v[200:203], v143 offset:38912
	ds_read_b128 v[204:207], v143 offset:39936
	global_load_lds_dwordx4 v134, s[24:25]
	s_mov_b32 m0, s45
	s_nop 0
	global_load_lds_dwordx4 v132, s[24:25]
	s_waitcnt vmcnt(8)
	s_waitcnt lgkmcnt(0)
	s_setprio 1
	s_barrier
	v_mfma_f32_16x16x32_bf16 v[124:127], v[144:147], v[176:179], v[124:127]
	v_mfma_f32_16x16x32_bf16 v[120:123], v[152:155], v[176:179], v[120:123]
	v_mfma_f32_16x16x32_bf16 v[108:111], v[144:147], v[184:187], v[108:111]
	v_mfma_f32_16x16x32_bf16 v[104:107], v[152:155], v[184:187], v[104:107]
	v_mfma_f32_16x16x32_bf16 v[92:95], v[144:147], v[192:195], v[92:95]
	v_mfma_f32_16x16x32_bf16 v[88:91], v[152:155], v[192:195], v[88:91]
	v_mfma_f32_16x16x32_bf16 v[76:79], v[144:147], v[200:203], v[76:79]
	v_mfma_f32_16x16x32_bf16 v[72:75], v[152:155], v[200:203], v[72:75]
	v_mfma_f32_16x16x32_bf16 v[124:127], v[148:151], v[180:183], v[124:127]
	v_mfma_f32_16x16x32_bf16 v[120:123], v[156:159], v[180:183], v[120:123]
	v_mfma_f32_16x16x32_bf16 v[108:111], v[148:151], v[188:191], v[108:111]
	v_mfma_f32_16x16x32_bf16 v[104:107], v[156:159], v[188:191], v[104:107]
	v_mfma_f32_16x16x32_bf16 v[92:95], v[148:151], v[196:199], v[92:95]
	v_mfma_f32_16x16x32_bf16 v[88:91], v[156:159], v[196:199], v[88:91]
	v_mfma_f32_16x16x32_bf16 v[76:79], v[148:151], v[204:207], v[76:79]
	v_mfma_f32_16x16x32_bf16 v[72:75], v[156:159], v[204:207], v[72:75]
	v_mfma_f32_16x16x32_bf16 v[116:119], v[160:163], v[176:179], v[116:119]
	v_mfma_f32_16x16x32_bf16 v[112:115], v[168:171], v[176:179], v[112:115]
	v_mfma_f32_16x16x32_bf16 v[100:103], v[160:163], v[184:187], v[100:103]
	v_mfma_f32_16x16x32_bf16 v[96:99], v[168:171], v[184:187], v[96:99]
	v_mfma_f32_16x16x32_bf16 v[84:87], v[160:163], v[192:195], v[84:87]
	v_mfma_f32_16x16x32_bf16 v[80:83], v[168:171], v[192:195], v[80:83]
	v_mfma_f32_16x16x32_bf16 v[68:71], v[160:163], v[200:203], v[68:71]
	v_mfma_f32_16x16x32_bf16 v[64:67], v[168:171], v[200:203], v[64:67]
	v_mfma_f32_16x16x32_bf16 v[116:119], v[164:167], v[180:183], v[116:119]
	v_mfma_f32_16x16x32_bf16 v[112:115], v[172:175], v[180:183], v[112:115]
	v_mfma_f32_16x16x32_bf16 v[100:103], v[164:167], v[188:191], v[100:103]
	v_mfma_f32_16x16x32_bf16 v[96:99], v[172:175], v[188:191], v[96:99]
	v_mfma_f32_16x16x32_bf16 v[84:87], v[164:167], v[196:199], v[84:87]
	v_mfma_f32_16x16x32_bf16 v[80:83], v[172:175], v[196:199], v[80:83]
	v_mfma_f32_16x16x32_bf16 v[68:71], v[164:167], v[204:207], v[68:71]
	v_mfma_f32_16x16x32_bf16 v[64:67], v[172:175], v[204:207], v[64:67]
	s_barrier
	s_setprio 0
	s_add_u32 s24, s30, 0x80
	s_addc_u32 s25, s31, 0
	s_add_i32 s36, s60, s40
	s_mov_b32 m0, s36
	ds_read_b128 v[176:179], v143 offset:49152
	ds_read_b128 v[180:183], v143 offset:50176
	ds_read_b128 v[184:187], v143 offset:51200
	ds_read_b128 v[188:191], v143 offset:52224
	ds_read_b128 v[192:195], v143 offset:53248
	ds_read_b128 v[196:199], v143 offset:54272
	ds_read_b128 v[200:203], v143 offset:55296
	ds_read_b128 v[204:207], v143 offset:56320
	global_load_lds_dwordx4 v128, s[24:25]
	s_add_i32 m0, s36, 0x2000
	v_lshl_add_u64 v[138:139], s[24:25], 0, v[130:131]
	s_add_u32 s24, s30, 0x100080
	s_addc_u32 s25, s31, 0
	s_add_i32 s30, s61, s40
	global_load_lds_dwordx4 v[138:139], off
	s_mov_b32 m0, s30
	s_nop 0
	global_load_lds_dwordx4 v128, s[24:25]
	s_add_i32 m0, s30, 0x2000
	s_nop 0
	global_load_lds_dwordx4 v130, s[24:25]
	s_waitcnt vmcnt(4)
	s_waitcnt lgkmcnt(0)
	s_setprio 1
	s_barrier
	v_mfma_f32_16x16x32_bf16 v[60:63], v[144:147], v[176:179], v[60:63]
	v_mfma_f32_16x16x32_bf16 v[56:59], v[152:155], v[176:179], v[56:59]
	v_mfma_f32_16x16x32_bf16 v[44:47], v[144:147], v[184:187], v[44:47]
	v_mfma_f32_16x16x32_bf16 v[40:43], v[152:155], v[184:187], v[40:43]
	v_mfma_f32_16x16x32_bf16 v[28:31], v[144:147], v[192:195], v[28:31]
	v_mfma_f32_16x16x32_bf16 v[24:27], v[152:155], v[192:195], v[24:27]
	v_mfma_f32_16x16x32_bf16 v[12:15], v[144:147], v[200:203], v[12:15]
	v_mfma_f32_16x16x32_bf16 v[8:11], v[152:155], v[200:203], v[8:11]
	v_mfma_f32_16x16x32_bf16 v[60:63], v[148:151], v[180:183], v[60:63]
	v_mfma_f32_16x16x32_bf16 v[56:59], v[156:159], v[180:183], v[56:59]
	v_mfma_f32_16x16x32_bf16 v[44:47], v[148:151], v[188:191], v[44:47]
	v_mfma_f32_16x16x32_bf16 v[40:43], v[156:159], v[188:191], v[40:43]
	v_mfma_f32_16x16x32_bf16 v[28:31], v[148:151], v[196:199], v[28:31]
	v_mfma_f32_16x16x32_bf16 v[24:27], v[156:159], v[196:199], v[24:27]
	v_mfma_f32_16x16x32_bf16 v[12:15], v[148:151], v[204:207], v[12:15]
	v_mfma_f32_16x16x32_bf16 v[8:11], v[156:159], v[204:207], v[8:11]
	v_mfma_f32_16x16x32_bf16 v[52:55], v[160:163], v[176:179], v[52:55]
	v_mfma_f32_16x16x32_bf16 v[48:51], v[168:171], v[176:179], v[48:51]
	v_mfma_f32_16x16x32_bf16 v[36:39], v[160:163], v[184:187], v[36:39]
	v_mfma_f32_16x16x32_bf16 v[32:35], v[168:171], v[184:187], v[32:35]
	v_mfma_f32_16x16x32_bf16 v[20:23], v[160:163], v[192:195], v[20:23]
	v_mfma_f32_16x16x32_bf16 v[16:19], v[168:171], v[192:195], v[16:19]
	v_mfma_f32_16x16x32_bf16 v[4:7], v[160:163], v[200:203], v[4:7]
	v_mfma_f32_16x16x32_bf16 v[0:3], v[168:171], v[200:203], v[0:3]
	v_mfma_f32_16x16x32_bf16 v[52:55], v[164:167], v[180:183], v[52:55]
	v_mfma_f32_16x16x32_bf16 v[48:51], v[172:175], v[180:183], v[48:51]
	v_mfma_f32_16x16x32_bf16 v[36:39], v[164:167], v[188:191], v[36:39]
	v_mfma_f32_16x16x32_bf16 v[32:35], v[172:175], v[188:191], v[32:35]
	v_mfma_f32_16x16x32_bf16 v[20:23], v[164:167], v[196:199], v[20:23]
	v_mfma_f32_16x16x32_bf16 v[16:19], v[172:175], v[196:199], v[16:19]
	v_mfma_f32_16x16x32_bf16 v[4:7], v[164:167], v[204:207], v[4:7]
	v_mfma_f32_16x16x32_bf16 v[0:3], v[172:175], v[204:207], v[0:3]
	s_barrier
	s_setprio 0
	s_add_i32 s59, s59, 2
	s_add_u32 s56, s56, 0x100
	s_addc_u32 s57, s57, 0
	s_cmp_gt_u32 s59, 61
	s_mov_b64 s[24:25], s[26:27]
	s_cbranch_scc0 .LBB0_3554
	s_and_b64 vcc, exec, s[10:11]
	s_cbranch_vccz .LBB0_3557
	s_barrier

; #define PG8_WAIT_V(n) asm volatile("s_waitcnt vmcnt(" #n ")" ::: "memory")
; #define PG8_WAIT_L(n) asm volatile("s_waitcnt lgkmcnt(" #n ")" ::: "memory")
; #define PG8_BAR __builtin_amdgcn_s_barrier()
; #define PG8_SCHED __builtin_amdgcn_sched_barrier(0)
;     ...
;             const char* a1 = cA + (size_t)(t + 1) * kstep;
;             const char* a2 = last ? nA : cA + (size_t)(t + 2) * kstep; const char* b2 = last ? nB : cB + (size_t)(t + 2) * kstep;
;             const char* a3 = a2 + kstep; const char* b3 = b2 + kstep;
;             if (last && has_next) S.a_ready(nxt);
;             if constexpr (SP2) {
;             PG8_LDB(B0, 0, 0); PG8_LDB(B1, 0, 1); PG8_SCHED; PG8_LDA(At, 0, 0); PG8_STAGE(PG8_SA(1, 1), a1 + hstepA, voffA);
;             PG8_WAIT_V(8); PG8_WAIT_L(0); PG8_BAR; PG8_MMA(0, 0, At, B0); PG8_MMA(0, 1, At, B1); PG8_BAR; PG8_SCHED;
;             if constexpr (!HALFU) PG8_LDA(At, 0, 1); PG8_STAGE(PG8_SB(0, 0), b2, voffB); PG8_STAGE(PG8_SB(0, 1), b2 + hstep, voffB); PG8_STAGE(PG8_SA(0, 0), a2, voffA);
;             PG8_WAIT_V(8); PG8_WAIT_L(0); PG8_BAR; if constexpr (!HALFU) { PG8_MMA(1, 0, At, B0); PG8_MMA(1, 1, At, B1); } PG8_BAR; PG8_SCHED;
.LBB0_3640:
	s_sub_u32 s98, s10, 0x158000
	s_subb_u32 s99, s11, 0
	s_mov_b32 m0, s42
	s_nop 0
	global_load_lds_dwordx4 v128, s[98:99]
	s_mov_b32 m0, s43
	s_nop 0
	global_load_lds_dwordx4 v130, s[98:99]
	ds_read_b128 v[142:145], v137
	ds_read_b128 v[146:149], v137 offset:1024
	ds_read_b128 v[150:153], v137 offset:2048
	ds_read_b128 v[154:157], v137 offset:3072
	ds_read_b128 v[158:161], v138
	ds_read_b128 v[162:165], v138 offset:1024
	ds_read_b128 v[166:169], v138 offset:2048
	ds_read_b128 v[170:173], v138 offset:3072
	s_cmpk_eq_i32 s55, 0x52
	s_cselect_b32 s28, s6, s51
	s_cselect_b32 s29, s7, s52
	s_cselect_b32 s26, s22, s53
	s_cselect_b32 s27, s23, s54
	s_add_u32 s24, s28, 0x80
	s_addc_u32 s25, s29, 0
	s_add_i32 m0, s33, 0xc000
	ds_read_b128 v[174:177], v139
	ds_read_b128 v[178:181], v139 offset:1024
	ds_read_b128 v[182:185], v139 offset:2048
	ds_read_b128 v[186:189], v139 offset:3072
	ds_read_b128 v[190:193], v139 offset:4096
	ds_read_b128 v[194:197], v139 offset:5120
	ds_read_b128 v[198:201], v139 offset:6144
	ds_read_b128 v[202:205], v139 offset:7168
	global_load_lds_dwordx4 v128, s[10:11]
	s_add_i32 m0, s33, 0xe000
	s_nop 0
	global_load_lds_dwordx4 v130, s[10:11]
	s_waitcnt vmcnt(8)
	s_waitcnt lgkmcnt(0)
	s_setprio 1
	s_barrier
	v_mfma_scale_f32_16x16x128_f8f6f4 v[124:127], v[142:149], v[174:181], v[124:127], v140, v140 op_sel_hi:[0,0,0]
	v_mfma_scale_f32_16x16x128_f8f6f4 v[120:123], v[150:157], v[174:181], v[120:123], v140, v140 op_sel_hi:[0,0,0]
	v_mfma_scale_f32_16x16x128_f8f6f4 v[112:115], v[142:149], v[182:189], v[112:115], v140, v140 op_sel_hi:[0,0,0]
	v_mfma_scale_f32_16x16x128_f8f6f4 v[104:107], v[150:157], v[182:189], v[104:107], v140, v140 op_sel_hi:[0,0,0]
	v_mfma_scale_f32_16x16x128_f8f6f4 v[96:99], v[142:149], v[190:197], v[96:99], v140, v140 op_sel_hi:[0,0,0]
	v_mfma_scale_f32_16x16x128_f8f6f4 v[206:209], v[150:157], v[190:197], v[88:91], v140, v140 op_sel_hi:[0,0,0]
	v_mfma_scale_f32_16x16x128_f8f6f4 v[210:213], v[142:149], v[198:205], v[80:83], v140, v140 op_sel_hi:[0,0,0]
	v_mfma_scale_f32_16x16x128_f8f6f4 v[214:217], v[150:157], v[198:205], v[72:75], v140, v140 op_sel_hi:[0,0,0]
	v_mfma_scale_f32_16x16x128_f8f6f4 v[116:119], v[158:165], v[174:181], v[116:119], v140, v140 op_sel_hi:[0,0,0]
	v_mfma_scale_f32_16x16x128_f8f6f4 v[108:111], v[166:173], v[174:181], v[108:111], v140, v140 op_sel_hi:[0,0,0]
	v_mfma_scale_f32_16x16x128_f8f6f4 v[100:103], v[158:165], v[182:189], v[100:103], v140, v140 op_sel_hi:[0,0,0]
	v_mfma_scale_f32_16x16x128_f8f6f4 v[174:177], v[166:173], v[182:189], v[92:95], v140, v140 op_sel_hi:[0,0,0]
	v_mfma_scale_f32_16x16x128_f8f6f4 v[178:181], v[158:165], v[190:197], v[84:87], v140, v140 op_sel_hi:[0,0,0]
	v_mfma_scale_f32_16x16x128_f8f6f4 v[182:185], v[166:173], v[190:197], v[76:79], v140, v140 op_sel_hi:[0,0,0]
	v_mfma_scale_f32_16x16x128_f8f6f4 v[186:189], v[158:165], v[198:205], v[68:71], v140, v140 op_sel_hi:[0,0,0]
	v_mfma_scale_f32_16x16x128_f8f6f4 v[190:193], v[166:173], v[198:205], v[64:67], v140, v140 op_sel_hi:[0,0,0]
	s_barrier
	s_setprio 0
	s_add_i32 s56, s45, s30
	s_mov_b32 m0, s56
	s_nop 1
	ds_read_b128 v[64:67], v139 offset:16384
	ds_read_b128 v[68:71], v139 offset:17408
	ds_read_b128 v[72:75], v139 offset:18432
	ds_read_b128 v[76:79], v139 offset:19456
	ds_read_b128 v[80:83], v139 offset:20480
	ds_read_b128 v[84:87], v139 offset:21504
	ds_read_b128 v[88:91], v139 offset:22528
	ds_read_b128 v[92:95], v139 offset:23552
	global_load_lds_dwordx4 v128, s[26:27]
	s_add_i32 m0, s56, 0x2000
	s_add_u32 s56, s26, 0x158000
	s_addc_u32 s57, s27, 0
	s_add_i32 s58, s46, s30
	global_load_lds_dwordx4 v130, s[26:27]
	s_mov_b32 m0, s58
	s_nop 0
	global_load_lds_dwordx4 v128, s[56:57]
	s_add_i32 m0, s58, 0x2000
	s_nop 0
	global_load_lds_dwordx4 v130, s[56:57]
	s_waitcnt vmcnt(4)
	s_waitcnt lgkmcnt(0)
	s_setprio 1
	s_barrier
	v_mfma_scale_f32_16x16x128_f8f6f4 v[60:63], v[142:149], v[64:71], v[60:63], v140, v140 op_sel_hi:[0,0,0]
	v_mfma_scale_f32_16x16x128_f8f6f4 v[56:59], v[150:157], v[64:71], v[56:59], v140, v140 op_sel_hi:[0,0,0]
	v_mfma_scale_f32_16x16x128_f8f6f4 v[48:51], v[142:149], v[72:79], v[48:51], v140, v140 op_sel_hi:[0,0,0]
	v_mfma_scale_f32_16x16x128_f8f6f4 v[194:197], v[150:157], v[72:79], v[40:43], v140, v140 op_sel_hi:[0,0,0]
	v_mfma_scale_f32_16x16x128_f8f6f4 v[198:201], v[142:149], v[80:87], v[32:35], v140, v140 op_sel_hi:[0,0,0]
	v_mfma_scale_f32_16x16x128_f8f6f4 v[202:205], v[150:157], v[80:87], v[24:27], v140, v140 op_sel_hi:[0,0,0]
	v_mfma_scale_f32_16x16x128_f8f6f4 v[218:221], v[142:149], v[88:95], v[16:19], v140, v140 op_sel_hi:[0,0,0]
	v_mfma_scale_f32_16x16x128_f8f6f4 v[222:225], v[150:157], v[88:95], v[8:11], v140, v140 op_sel_hi:[0,0,0]
	v_mfma_scale_f32_16x16x128_f8f6f4 v[52:55], v[158:165], v[64:71], v[52:55], v140, v140 op_sel_hi:[0,0,0]
	v_mfma_scale_f32_16x16x128_f8f6f4 v[226:229], v[166:173], v[64:71], v[44:47], v140, v140 op_sel_hi:[0,0,0]
	v_mfma_scale_f32_16x16x128_f8f6f4 v[230:233], v[158:165], v[72:79], v[36:39], v140, v140 op_sel_hi:[0,0,0]
	v_mfma_scale_f32_16x16x128_f8f6f4 v[234:237], v[166:173], v[72:79], v[28:31], v140, v140 op_sel_hi:[0,0,0]
	v_mfma_scale_f32_16x16x128_f8f6f4 v[238:241], v[158:165], v[80:87], v[20:23], v140, v140 op_sel_hi:[0,0,0]
	v_mfma_scale_f32_16x16x128_f8f6f4 v[242:245], v[166:173], v[80:87], v[12:15], v140, v140 op_sel_hi:[0,0,0]
	v_mfma_scale_f32_16x16x128_f8f6f4 v[246:249], v[158:165], v[88:95], v[4:7], v140, v140 op_sel_hi:[0,0,0]
	v_mfma_scale_f32_16x16x128_f8f6f4 v[250:253], v[166:173], v[88:95], v[0:3], v140, v140 op_sel_hi:[0,0,0]
	s_barrier
; #define PG8_WAIT_V(n) asm volatile("s_waitcnt vmcnt(" #n ")" ::: "memory")
; #define PG8_WAIT_L(n) asm volatile("s_waitcnt lgkmcnt(" #n ")" ::: "memory")
; #define PG8_BAR __builtin_amdgcn_s_barrier()
; #define PG8_SCHED __builtin_amdgcn_sched_barrier(0)
;     ...
;         for (int t = 0; t < nt; t += 2) {
;     ...
;             PG8_LDB(B0, 1, 0); PG8_LDB(B1, 1, 1); PG8_SCHED; PG8_LDA(At, 1, 0); PG8_STAGE(PG8_SA(0, 1), a2 + hstepA, voffA);
;             PG8_WAIT_V(8); PG8_WAIT_L(0); PG8_BAR; PG8_MMA(0, 0, At, B0); PG8_MMA(0, 1, At, B1); PG8_BAR; PG8_SCHED;
;             if constexpr (!HALFU) PG8_LDA(At, 1, 1); PG8_STAGE(PG8_SB(1, 0), b3, voffB); PG8_STAGE(PG8_SB(1, 1), b3 + hstep, voffB); PG8_STAGE(PG8_SA(1, 0), a3, voffA);
;             PG8_WAIT_V(8); PG8_WAIT_L(0); PG8_BAR; if constexpr (!HALFU) { PG8_MMA(1, 0, At, B0); PG8_MMA(1, 1, At, B1); } PG8_BAR; PG8_SCHED;
	s_setprio 0
	s_mov_b32 m0, s33
	s_nop 0
	global_load_lds_dwordx4 v128, s[28:29]
	s_mov_b32 m0, s36
	s_nop 0
	global_load_lds_dwordx4 v130, s[28:29]
	s_add_i32 s56, 0, 0x18000
	s_add_i32 s57, 0, 0x1c000
	s_nop 0
	v_add_u32_e32 v12, s56, v136
	v_add_u32_e32 v16, s57, v136
	ds_read_b128 v[0:3], v12
	ds_read_b128 v[4:7], v12 offset:1024
	ds_read_b128 v[8:11], v12 offset:2048
	ds_read_b128 v[12:15], v12 offset:3072
	ds_read_b128 v[142:145], v16
	ds_read_b128 v[146:149], v16 offset:1024
	ds_read_b128 v[150:153], v16 offset:2048
	ds_read_b128 v[154:157], v16 offset:3072
	s_add_u32 s28, s28, 0x158000
	s_addc_u32 s29, s29, 0
	s_mov_b32 m0, s37
	ds_read_b128 v[16:19], v139 offset:32768
	ds_read_b128 v[20:23], v139 offset:33792
	ds_read_b128 v[24:27], v139 offset:34816
	ds_read_b128 v[28:31], v139 offset:35840
	ds_read_b128 v[32:35], v139 offset:36864
	ds_read_b128 v[36:39], v139 offset:37888
	ds_read_b128 v[40:43], v139 offset:38912
	ds_read_b128 v[44:47], v139 offset:39936
	global_load_lds_dwordx4 v128, s[28:29]
	s_mov_b32 m0, s38
	s_nop 0
	global_load_lds_dwordx4 v130, s[28:29]
	s_waitcnt vmcnt(8)
	s_waitcnt lgkmcnt(0)
	s_setprio 1
	s_barrier
	v_mfma_scale_f32_16x16x128_f8f6f4 v[124:127], v[0:7], v[16:23], v[124:127], v140, v140 op_sel_hi:[0,0,0]
	v_mfma_scale_f32_16x16x128_f8f6f4 v[120:123], v[8:15], v[16:23], v[120:123], v140, v140 op_sel_hi:[0,0,0]
	v_mfma_scale_f32_16x16x128_f8f6f4 v[112:115], v[0:7], v[24:31], v[112:115], v140, v140 op_sel_hi:[0,0,0]
	v_mfma_scale_f32_16x16x128_f8f6f4 v[104:107], v[8:15], v[24:31], v[104:107], v140, v140 op_sel_hi:[0,0,0]
	v_mfma_scale_f32_16x16x128_f8f6f4 v[96:99], v[0:7], v[32:39], v[96:99], v140, v140 op_sel_hi:[0,0,0]
	v_mfma_scale_f32_16x16x128_f8f6f4 v[88:91], v[8:15], v[32:39], v[206:209], v140, v140 op_sel_hi:[0,0,0]
	v_mfma_scale_f32_16x16x128_f8f6f4 v[80:83], v[0:7], v[40:47], v[210:213], v140, v140 op_sel_hi:[0,0,0]
	v_mfma_scale_f32_16x16x128_f8f6f4 v[72:75], v[8:15], v[40:47], v[214:217], v140, v140 op_sel_hi:[0,0,0]
	v_mfma_scale_f32_16x16x128_f8f6f4 v[116:119], v[142:149], v[16:23], v[116:119], v140, v140 op_sel_hi:[0,0,0]
	v_mfma_scale_f32_16x16x128_f8f6f4 v[108:111], v[150:157], v[16:23], v[108:111], v140, v140 op_sel_hi:[0,0,0]
	v_mfma_scale_f32_16x16x128_f8f6f4 v[100:103], v[142:149], v[24:31], v[100:103], v140, v140 op_sel_hi:[0,0,0]
	v_mfma_scale_f32_16x16x128_f8f6f4 v[92:95], v[150:157], v[24:31], v[174:177], v140, v140 op_sel_hi:[0,0,0]
	v_mfma_scale_f32_16x16x128_f8f6f4 v[84:87], v[142:149], v[32:39], v[178:181], v140, v140 op_sel_hi:[0,0,0]
	v_mfma_scale_f32_16x16x128_f8f6f4 v[76:79], v[150:157], v[32:39], v[182:185], v140, v140 op_sel_hi:[0,0,0]
	v_mfma_scale_f32_16x16x128_f8f6f4 v[68:71], v[142:149], v[40:47], v[186:189], v140, v140 op_sel_hi:[0,0,0]
	v_mfma_scale_f32_16x16x128_f8f6f4 v[64:67], v[150:157], v[40:47], v[190:193], v140, v140 op_sel_hi:[0,0,0]
	s_barrier
	s_setprio 0
	s_add_u32 s28, s26, 0x80
	s_addc_u32 s29, s27, 0
	s_add_i32 s56, s56, s30
	s_mov_b32 m0, s56
	ds_read_b128 v[158:161], v139 offset:49152
	ds_read_b128 v[162:165], v139 offset:50176
	ds_read_b128 v[166:169], v139 offset:51200
	ds_read_b128 v[170:173], v139 offset:52224
	ds_read_b128 v[174:177], v139 offset:53248
	ds_read_b128 v[178:181], v139 offset:54272
	ds_read_b128 v[182:185], v139 offset:55296
	ds_read_b128 v[186:189], v139 offset:56320
	global_load_lds_dwordx4 v128, s[28:29]
	s_add_i32 m0, s56, 0x2000
	s_add_u32 s26, s26, 0x158080
	v_lshl_add_u64 v[16:17], s[28:29], 0, v[130:131]
	s_addc_u32 s27, s27, 0
	s_add_i32 s28, s57, s30
	global_load_lds_dwordx4 v[16:17], off
	s_mov_b32 m0, s28
	s_nop 0
	global_load_lds_dwordx4 v128, s[26:27]
	s_add_i32 m0, s28, 0x2000
	s_nop 0
	global_load_lds_dwordx4 v130, s[26:27]
	s_waitcnt vmcnt(4)
	s_waitcnt lgkmcnt(0)
	s_setprio 1
	s_barrier
	v_mfma_scale_f32_16x16x128_f8f6f4 v[60:63], v[0:7], v[158:165], v[60:63], v140, v140 op_sel_hi:[0,0,0]
	v_mfma_scale_f32_16x16x128_f8f6f4 v[56:59], v[8:15], v[158:165], v[56:59], v140, v140 op_sel_hi:[0,0,0]
	v_mfma_scale_f32_16x16x128_f8f6f4 v[48:51], v[0:7], v[166:173], v[48:51], v140, v140 op_sel_hi:[0,0,0]
	v_mfma_scale_f32_16x16x128_f8f6f4 v[40:43], v[8:15], v[166:173], v[194:197], v140, v140 op_sel_hi:[0,0,0]
	v_mfma_scale_f32_16x16x128_f8f6f4 v[32:35], v[0:7], v[174:181], v[198:201], v140, v140 op_sel_hi:[0,0,0]
	v_mfma_scale_f32_16x16x128_f8f6f4 v[24:27], v[8:15], v[174:181], v[202:205], v140, v140 op_sel_hi:[0,0,0]
	v_mfma_scale_f32_16x16x128_f8f6f4 v[16:19], v[0:7], v[182:189], v[218:221], v140, v140 op_sel_hi:[0,0,0]
	v_mfma_scale_f32_16x16x128_f8f6f4 v[8:11], v[8:15], v[182:189], v[222:225], v140, v140 op_sel_hi:[0,0,0]
	v_mfma_scale_f32_16x16x128_f8f6f4 v[52:55], v[142:149], v[158:165], v[52:55], v140, v140 op_sel_hi:[0,0,0]
	v_mfma_scale_f32_16x16x128_f8f6f4 v[44:47], v[150:157], v[158:165], v[226:229], v140, v140 op_sel_hi:[0,0,0]
	v_mfma_scale_f32_16x16x128_f8f6f4 v[36:39], v[142:149], v[166:173], v[230:233], v140, v140 op_sel_hi:[0,0,0]
	v_mfma_scale_f32_16x16x128_f8f6f4 v[28:31], v[150:157], v[166:173], v[234:237], v140, v140 op_sel_hi:[0,0,0]
	v_mfma_scale_f32_16x16x128_f8f6f4 v[20:23], v[142:149], v[174:181], v[238:241], v140, v140 op_sel_hi:[0,0,0]
	v_mfma_scale_f32_16x16x128_f8f6f4 v[12:15], v[150:157], v[174:181], v[242:245], v140, v140 op_sel_hi:[0,0,0]
	v_mfma_scale_f32_16x16x128_f8f6f4 v[4:7], v[142:149], v[182:189], v[246:249], v140, v140 op_sel_hi:[0,0,0]
	v_mfma_scale_f32_16x16x128_f8f6f4 v[0:3], v[150:157], v[182:189], v[250:253], v140, v140 op_sel_hi:[0,0,0]
	s_barrier
	s_setprio 0
	s_add_i32 s55, s55, 2
	s_add_u32 s51, s51, 0x100
	s_addc_u32 s52, s52, 0
	s_add_u32 s53, s53, 0x100
	s_addc_u32 s54, s54, 0
	s_add_u32 s10, s10, 0x100
	s_addc_u32 s11, s11, 0
	s_cmpk_gt_u32 s55, 0x53
	s_cbranch_scc0 .LBB0_3640
	s_and_b64 vcc, exec, s[12:13]
	s_cbranch_vccz .LBB0_3643
	s_barrier
